# conv f32 k/v stores rewritten as whole 128-byte lines (two 8-byte loads per lane), no nt
# speedup vs baseline: 1.0235x; 1.0192x over previous
; #define LAS __attribute__((address_space(3)))
; #define ATT_DMA(jt, slot) do { glds16(ksrc + (size_t)(jt) * 64 * D, (unsigned)__builtin_amdgcn_readfirstlane(lds0 + A_K + (slot) * 8192 + wid * 1024)); \
;                                glds16(vsrc + (size_t)(jt) * 64 * D, (unsigned)__builtin_amdgcn_readfirstlane(lds0 + A_V + (slot) * 8192 + wid * 1024)); } while (0)
; __device__ __forceinline__ void conv_load(ConvRegs& c, const Args& a, size_t rowq, int col, int lane) {
; #pragma unroll
;     for (int i = 0; i < 4; ++i) { const size_t grow = rowq + i * 8 + (lane >> 3);
;         c.k[i] = *(const u32x4*)((const bf16*)(a.ws + WS_K) + grow * D + col + (lane & 7) * 8); c.v[i] = *(const u32x4*)((const bf16*)(a.ws + WS_V) + grow * D + col + (lane & 7) * 8); }
; __device__ __forceinline__ void prompt_unit_sb(const Args& a, int l, int b, int h, int qb, LAS unsigned char* lds) {
;     ...
;     f16x8 T00, T01; make_tri(T00, T01, r32, hi);
;     const int q0 = qb * 256, jb = q0 / 64, jd = jb + (wid >> 1);
;     const int col = W + h * HD;
;     const size_t rowb = (size_t)b * T;
;     const bf16* Kh = (const bf16*)(a.ws + WS_K) + rowb * D + col; const bf16* Vh = (const bf16*)(a.ws + WS_V) + rowb * D + col;
;     const unsigned lds0 = (unsigned)(uintptr_t)lds;
;     const bf16* ksrc = Kh + (size_t)lane * D + wid * 8;
;     const bf16* vsrc = Vh + (size_t)(16 * (wid & 3) + (lane >> 2)) * D + (wid >> 2) * 32 + (lane & 3) * 8;
;     ...
;     ATT_DMA(jb + 3); ATT_DMA(jb + 2); ATT_DMA(jb + 1); ATT_DMA(jb);
;     if (jb >= 4) { ATT_DMA(jb - 1); ATT_DMA(jb - 2); ATT_DMA(jb - 3); }
;     bf16x8 qr[4];
;     { const bf16* Qw = (const bf16*)(a.ws + WS_Q) + (rowb + q0 + wid * 32 + r32) * D + col;
; #pragma unroll
;       for (int d0 = 0; d0 < 4; ++d0) qr[d0] = *(const bf16x8*)(Qw + d0 * 16 + hi * 8); }
;     const lds_cptr vp0 = (lds_cptr)lds + B_V + ((lane >> 4) & 1) * 32 + (lane & 3) * 8 + (4 * hi + ((lane & 15) >> 2)) * 64;
;     const int qlim = 32 * (wid & 1) + r32;
;     LAS float* wsf = (LAS float*)(lds + B_WSF) + wid * 64;
;     LAS unsigned* flags = (LAS unsigned*)(lds + B_FLAG);
;     FoxState st; st.m = 0.f; st.l = 0.f; st.mq = (bf16x8){}; st.o[0] = (f32x16){}; st.o[1] = (f32x16){};
;     float R = 0.f; bool done = false;
;     { ConvRegs cv; conv_load(cv, a, rowb + q0 + wid * 32, col, lane); conv_store<1>(cv, a, l, h, rowb + q0 + wid * 32, lane); }
.LBB0_267:
	s_lshl_b32 s0, s4, 8
	s_ashr_i32 s4, s6, 7
	s_ashr_i32 s1, s0, 31
	v_lshrrev_b32_e32 v54, 5, v2
	s_add_u32 s0, s0, s7
	v_and_b32_e32 v169, 31, v19
	v_lshlrev_b32_e32 v55, 2, v54
	s_addc_u32 s1, s1, 0
	s_lshl_b32 s6, s82, 5
	v_cmp_lt_u32_e32 vcc, v55, v169
	v_or_b32_e32 v56, 16, v55
	s_ashr_i32 s7, s6, 31
	v_cndmask_b32_e64 v14, v181, 0, vcc
	v_cmp_lt_u32_e32 vcc, v56, v169
	v_or_b32_e32 v58, 1, v55
	s_add_u32 s78, s0, s6
	v_cndmask_b32_e64 v26, v181, 0, vcc
	v_or_b32_e32 v57, 2, v55
	v_cmp_lt_u32_e32 vcc, v58, v169
	s_addc_u32 s79, s1, s7
	v_or_b32_e32 v60, 17, v55
	v_cndmask_b32_e64 v15, v181, 0, vcc
	v_cmp_lt_u32_e32 vcc, v57, v169
	v_or_b32_e32 v160, s78, v169
	v_mov_b32_e32 v161, s79
	v_readlane_b32 s0, v242, 22
	v_cndmask_b32_e64 v16, v181, 0, vcc
	v_or_b32_e32 v59, 18, v55
	v_cmp_lt_u32_e32 vcc, v60, v169
	v_lshlrev_b64 v[6:7], 11, v[160:161]
	v_readlane_b32 s1, v242, 23
	v_cndmask_b32_e64 v27, v181, 0, vcc
	v_cmp_lt_u32_e32 vcc, v59, v169
	v_or_b32_e32 v62, 3, v55
	v_lshl_add_u64 v[6:7], s[0:1], 0, v[6:7]
	s_lshl_b32 s0, s5, 1
	s_mov_b32 s1, s87
	v_lshrrev_b32_e32 v1, 3, v2
	v_cndmask_b32_e64 v20, v181, 0, vcc
	v_or_b32_e32 v61, 8, v55
	v_cmp_lt_u32_e32 vcc, v62, v169
	v_lshl_add_u64 v[6:7], v[6:7], 0, s[0:1]
	v_lshlrev_b32_e32 v4, 4, v54
	v_or_b32_e32 v160, s78, v1
	v_cndmask_b32_e64 v17, v181, 0, vcc
	v_cmp_lt_u32_e32 vcc, v61, v169
	v_or_b32_e32 v64, 19, v55
	v_lshl_add_u64 v[24:25], v[6:7], 0, v[4:5]
	v_lshlrev_b32_e32 v4, 3, v2
	v_lshlrev_b64 v[166:167], 11, v[160:161]
	v_readlane_b32 s8, v242, 20
	v_cndmask_b32_e64 v21, v181, 0, vcc
	v_or_b32_e32 v63, 24, v55
	v_cmp_lt_u32_e32 vcc, v64, v169
	v_and_b32_e32 v168, 56, v4
	v_lshl_add_u64 v[6:7], s[94:95], 0, v[166:167]
	v_readlane_b32 s9, v242, 21
	v_cndmask_b32_e64 v22, v181, 0, vcc
	v_cmp_lt_u32_e32 vcc, v63, v169
	v_or_b32_e32 v65, 10, v55
	v_lshl_add_u64 v[6:7], v[6:7], 0, s[0:1]
	v_mov_b32_e32 v4, v168
	v_lshl_add_u64 v[10:11], s[8:9], 0, v[166:167]
	v_cndmask_b32_e64 v23, v181, 0, vcc
	v_or_b32_e32 v66, 9, v55
	v_lshl_add_u64 v[6:7], v[6:7], 0, v[4:5]
	v_cmp_lt_u32_e32 vcc, v65, v169
	v_lshl_add_u64 v[10:11], v[10:11], 0, s[0:1]
	global_load_dwordx2 v[8:9], v[6:7], off offset:1088
	global_load_dwordx2 v[6:7], v[6:7], off offset:1024
	v_cndmask_b32_e64 v28, v181, 0, vcc
	v_cmp_lt_u32_e32 vcc, v66, v169
	v_or_b32_e32 v67, 26, v55
	v_lshl_add_u64 v[10:11], v[10:11], 0, v[4:5]
	v_cndmask_b32_e64 v29, v181, 0, vcc
	v_or_b32_e32 v68, 25, v55
	global_load_dwordx2 v[12:13], v[10:11], off offset:1088
	global_load_dwordx2 v[10:11], v[10:11], off offset:1024
	v_cmp_lt_u32_e32 vcc, v67, v169
	v_or_b32_e32 v69, 11, v55
	v_or_b32_e32 v44, 0x4000, v166
	v_cndmask_b32_e64 v30, v181, 0, vcc
	v_cmp_lt_u32_e32 vcc, v68, v169
	v_mov_b32_e32 v45, v167
	v_or_b32_e32 v70, 27, v55
	v_cndmask_b32_e64 v31, v181, 0, vcc
	v_cmp_lt_u32_e32 vcc, v69, v169
	v_pack_b32_f16 v116, v14, v15
	v_lshl_add_u64 v[14:15], s[94:95], 0, v[44:45]
	v_cndmask_b32_e64 v32, v181, 0, vcc
	v_cmp_lt_u32_e32 vcc, v70, v169
	v_pack_b32_f16 v118, v21, v29
	v_lshl_add_u64 v[14:15], v[14:15], 0, s[0:1]
	v_cndmask_b32_e64 v21, v181, 0, vcc
	v_lshl_add_u64 v[14:15], v[14:15], 0, v[4:5]
	v_pack_b32_f16 v121, v20, v22
	v_pack_b32_f16 v123, v30, v21
	v_lshl_add_u64 v[20:21], s[8:9], 0, v[44:45]
	v_pack_b32_f16 v117, v16, v17
	global_load_dwordx2 v[16:17], v[14:15], off offset:1088
	global_load_dwordx2 v[14:15], v[14:15], off offset:1024
	v_lshl_add_u64 v[20:21], v[20:21], 0, s[0:1]
	v_lshl_add_u64 v[20:21], v[20:21], 0, v[4:5]
	v_pack_b32_f16 v122, v23, v31
	global_load_dwordx2 v[22:23], v[20:21], off offset:1088
	global_load_dwordx2 v[20:21], v[20:21], off offset:1024
	s_nop 0
	global_load_dwordx4 v[124:127], v[24:25], off offset:1024
	global_load_dwordx4 v[128:131], v[24:25], off offset:1056
	global_load_dwordx4 v[132:135], v[24:25], off offset:1088
	global_load_dwordx4 v[136:139], v[24:25], off offset:1120
	v_lshlrev_b32_e32 v24, 1, v19
	v_and_b32_e32 v24, 32, v24
	s_add_i32 s7, 0, 0x10000
	v_or_b32_e32 v46, 0x8000, v166
	v_mov_b32_e32 v47, v167
	v_add3_u32 v3, s7, v24, v3
	v_lshl_add_u64 v[24:25], s[94:95], 0, v[46:47]
	v_lshlrev_b32_e32 v29, 4, v19
	v_pack_b32_f16 v119, v28, v32
	v_lshlrev_b32_e32 v28, 8, v54
	v_lshl_add_u64 v[24:25], v[24:25], 0, s[0:1]
	v_and_b32_e32 v29, 0xc0, v29
	v_lshl_add_u64 v[24:25], v[24:25], 0, v[4:5]
	v_add3_u32 v170, v3, v28, v29
	v_lshl_add_u64 v[28:29], s[8:9], 0, v[46:47]
	v_pack_b32_f16 v120, v26, v27
	global_load_dwordx2 v[26:27], v[24:25], off offset:1088
	global_load_dwordx2 v[24:25], v[24:25], off offset:1024
	v_lshl_add_u64 v[28:29], v[28:29], 0, s[0:1]
	v_lshl_add_u64 v[28:29], v[28:29], 0, v[4:5]
	global_load_dwordx2 v[30:31], v[28:29], off offset:1088
	global_load_dwordx2 v[28:29], v[28:29], off offset:1024
	v_or_b32_e32 v48, 0xc000, v166
	v_mov_b32_e32 v49, v167
	v_lshl_add_u64 v[32:33], s[94:95], 0, v[48:49]
	v_lshl_add_u64 v[34:35], s[8:9], 0, v[48:49]
	v_lshl_add_u64 v[32:33], v[32:33], 0, s[0:1]
	v_lshl_add_u64 v[34:35], v[34:35], 0, s[0:1]
	v_lshl_add_u64 v[32:33], v[32:33], 0, v[4:5]
	v_lshl_add_u64 v[36:37], v[34:35], 0, v[4:5]
	global_load_dwordx2 v[34:35], v[32:33], off offset:1088
	global_load_dwordx2 v[32:33], v[32:33], off offset:1024
	s_nop 0
	global_load_dwordx2 v[38:39], v[36:37], off offset:1088
	global_load_dwordx2 v[36:37], v[36:37], off offset:1024
	v_and_or_b32 v3, s6, 32, v169
	v_readlane_b32 s6, v242, 24
	v_readlane_b32 s7, v242, 25
	s_lshl_b32 s92, s5, 2
	s_mov_b32 s93, s87
	v_lshl_add_u64 v[40:41], s[6:7], 0, v[166:167]
	v_readlane_b32 s8, v242, 26
	v_lshl_add_u64 v[40:41], v[40:41], 0, s[92:93]
	v_lshlrev_b32_e32 v4, 1, v168
	v_readlane_b32 s9, v242, 27
	v_lshl_add_u64 v[50:51], v[40:41], 0, v[4:5]
	v_lshlrev_b32_e32 v171, 10, v54
	v_lshl_add_u64 v[40:41], s[8:9], 0, v[166:167]
	v_lshl_add_u64 v[40:41], v[40:41], 0, s[92:93]
	v_lshl_add_u64 v[52:53], v[40:41], 0, v[4:5]
	s_lshl_b32 s1, s82, 2
	s_waitcnt vmcnt(0)
; #define LAS __attribute__((address_space(3)))
; __device__ __forceinline__ float bflo(unsigned w) { return __uint_as_float(w << 16); }
; __device__ __forceinline__ float bfhi(unsigned w) { return __uint_as_float(w & 0xffff0000u); }
; #define ATT_WAIT_BAR_N(N) asm volatile("s_waitcnt vmcnt(" #N ") lgkmcnt(0)\n\ts_barrier" ::: "memory")
; template <int TYPE>
; __device__ __forceinline__ void conv_store(const ConvRegs& c, const Args& a, int l, int h, size_t rowq, int lane) {
; #pragma unroll
;     for (int i = 0; i < 4; ++i) { const size_t grow = rowq + i * 8 + (lane >> 3);
;         float* ko = a.out + (TYPE == 0 ? O_FKP : O_SKP) + ((size_t)l * MP + grow) * W + h * HD + (lane & 7) * 8;
;         float* vo = a.out + (TYPE == 0 ? O_FVP : O_SVP) + ((size_t)l * MP + grow) * W + h * HD + (lane & 7) * 8;
;         const u32x4 kw = c.k[i], vw = c.v[i];
;         __builtin_nontemporal_store((f32x4){bflo(kw.x), bfhi(kw.x), bflo(kw.y), bfhi(kw.y)}, (f32x4*)ko); __builtin_nontemporal_store((f32x4){bflo(kw.z), bfhi(kw.z), bflo(kw.w), bfhi(kw.w)}, (f32x4*)(ko + 4));
;         __builtin_nontemporal_store((f32x4){bflo(vw.x), bfhi(vw.x), bflo(vw.y), bfhi(vw.y)}, (f32x4*)vo); __builtin_nontemporal_store((f32x4){bflo(vw.z), bfhi(vw.z), bflo(vw.w), bfhi(vw.w)}, (f32x4*)(vo + 4)); }
; }
; __device__ __forceinline__ void prompt_unit_sb(const Args& a, int l, int b, int h, int qb, LAS unsigned char* lds) {
;     ...
;     const lds_cptr vp0 = (lds_cptr)lds + B_V + ((lane >> 4) & 1) * 32 + (lane & 3) * 8 + (4 * hi + ((lane & 15) >> 2)) * 64;
;     const int qlim = 32 * (wid & 1) + r32;
;     LAS float* wsf = (LAS float*)(lds + B_WSF) + wid * 64;
;     LAS unsigned* flags = (LAS unsigned*)(lds + B_FLAG);
;     FoxState st; st.m = 0.f; st.l = 0.f; st.mq = (bf16x8){}; st.o[0] = (f32x16){}; st.o[1] = (f32x16){};
;     float R = 0.f; bool done = false;
;     { ConvRegs cv; conv_load(cv, a, rowb + q0 + wid * 32, col, lane); conv_store<1>(cv, a, l, h, rowb + q0 + wid * 32, lane); }
;     for (int it = 0; ; ++it) {
;         const int need = jb - it;
;         if (need >= 3) ATT_WAIT_BAR_N(6); else if (need == 2) ATT_WAIT_BAR_N(4); else if (need == 1) ATT_WAIT_BAR_N(2); else ATT_WAIT_BAR_N(0);
	v_lshlrev_b32_e32 v40, 16, v6
	v_and_b32_e32 v41, 0xffff0000, v6
	v_lshlrev_b32_e32 v42, 16, v7
	v_and_b32_e32 v43, 0xffff0000, v7
	v_lshlrev_b32_e32 v6, 16, v8
	v_and_b32_e32 v7, 0xffff0000, v8
	v_lshlrev_b32_e32 v8, 16, v9
	v_and_b32_e32 v9, 0xffff0000, v9
	global_store_dwordx4 v[50:51], v[6:9], off offset:128
	global_store_dwordx4 v[50:51], v[40:43], off
	s_add_i32 s1, s1, 0
	v_lshlrev_b32_e32 v6, 16, v10
	v_and_b32_e32 v7, 0xffff0000, v10
	v_lshlrev_b32_e32 v8, 16, v11
	v_and_b32_e32 v9, 0xffff0000, v11
	global_store_dwordx4 v[52:53], v[6:9], off
	v_cmp_lt_u32_e64 s[10:11], v58, v3
	v_cmp_lt_u32_e64 s[14:15], v57, v3
	v_lshlrev_b32_e32 v6, 16, v12
	v_and_b32_e32 v7, 0xffff0000, v12
	v_lshlrev_b32_e32 v8, 16, v13
	v_and_b32_e32 v9, 0xffff0000, v13
	global_store_dwordx4 v[52:53], v[6:9], off offset:128
	v_cmp_lt_u32_e64 s[18:19], v62, v3
	v_cmp_lt_u32_e64 s[22:23], v61, v3
	v_lshl_add_u64 v[6:7], s[6:7], 0, v[44:45]
	v_lshl_add_u64 v[6:7], v[6:7], 0, s[92:93]
	v_lshl_add_u64 v[10:11], v[6:7], 0, v[4:5]
	v_lshl_add_u64 v[6:7], s[8:9], 0, v[44:45]
	v_lshl_add_u64 v[6:7], v[6:7], 0, s[92:93]
	v_lshl_add_u64 v[12:13], v[6:7], 0, v[4:5]
	v_lshlrev_b32_e32 v6, 16, v14
	v_and_b32_e32 v7, 0xffff0000, v14
	v_lshlrev_b32_e32 v8, 16, v15
	v_and_b32_e32 v9, 0xffff0000, v15
	global_store_dwordx4 v[10:11], v[6:9], off
	v_cmp_lt_u32_e64 s[26:27], v66, v3
	v_cmp_lt_u32_e64 s[30:31], v65, v3
	v_lshlrev_b32_e32 v6, 16, v16
	v_and_b32_e32 v7, 0xffff0000, v16
	v_lshlrev_b32_e32 v8, 16, v17
	v_and_b32_e32 v9, 0xffff0000, v17
	global_store_dwordx4 v[10:11], v[6:9], off offset:128
	v_mov_b32_e32 v16, v5
	v_mov_b32_e32 v17, v5
	v_lshlrev_b32_e32 v6, 16, v20
	v_and_b32_e32 v7, 0xffff0000, v20
	v_lshlrev_b32_e32 v8, 16, v21
	v_and_b32_e32 v9, 0xffff0000, v21
	global_store_dwordx4 v[12:13], v[6:9], off
	v_and_or_b32 v20, v183, 64, v169
	v_cmp_lt_u32_e64 s[36:37], v69, v3
	v_lshlrev_b32_e32 v6, 16, v22
	v_and_b32_e32 v7, 0xffff0000, v22
	v_lshlrev_b32_e32 v8, 16, v23
	v_and_b32_e32 v9, 0xffff0000, v23
	global_store_dwordx4 v[12:13], v[6:9], off offset:128
	v_cmp_lt_u32_e64 s[40:41], v56, v3
	v_cmp_lt_u32_e64 s[44:45], v60, v3
	v_lshl_add_u64 v[6:7], s[6:7], 0, v[46:47]
	v_lshl_add_u64 v[6:7], v[6:7], 0, s[92:93]
	v_lshl_add_u64 v[10:11], v[6:7], 0, v[4:5]
	v_lshl_add_u64 v[6:7], s[8:9], 0, v[46:47]
	v_lshl_add_u64 v[6:7], v[6:7], 0, s[92:93]
	v_lshl_add_u64 v[12:13], v[6:7], 0, v[4:5]
	v_lshlrev_b32_e32 v6, 16, v24
	v_and_b32_e32 v7, 0xffff0000, v24
	v_lshlrev_b32_e32 v8, 16, v25
	v_and_b32_e32 v9, 0xffff0000, v25
	global_store_dwordx4 v[10:11], v[6:9], off
	v_cmp_lt_u32_e64 s[48:49], v59, v3
	v_cmp_lt_u32_e64 s[52:53], v64, v3
	v_lshlrev_b32_e32 v6, 16, v26
	v_and_b32_e32 v7, 0xffff0000, v26
	v_lshlrev_b32_e32 v8, 16, v27
	v_and_b32_e32 v9, 0xffff0000, v27
	global_store_dwordx4 v[10:11], v[6:9], off offset:128
	v_cmp_lt_u32_e64 s[56:57], v63, v3
	v_cmp_lt_u32_e64 s[60:61], v68, v3
	v_lshlrev_b32_e32 v6, 16, v28
	v_and_b32_e32 v7, 0xffff0000, v28
	v_lshlrev_b32_e32 v8, 16, v29
	v_and_b32_e32 v9, 0xffff0000, v29
	global_store_dwordx4 v[12:13], v[6:9], off
	v_cmp_lt_u32_e64 s[64:65], v67, v3
	v_cmp_lt_u32_e64 s[68:69], v70, v3
	v_lshlrev_b32_e32 v6, 16, v30
	v_and_b32_e32 v7, 0xffff0000, v30
	v_lshlrev_b32_e32 v8, 16, v31
	v_and_b32_e32 v9, 0xffff0000, v31
	global_store_dwordx4 v[12:13], v[6:9], off offset:128
	v_cmp_eq_u32_e64 s[72:73], 0, v2
	s_lshl_b32 s5, s3, 15
	v_lshl_add_u64 v[6:7], s[6:7], 0, v[48:49]
	v_lshl_add_u64 v[6:7], v[6:7], 0, s[92:93]
	v_lshl_add_u64 v[10:11], v[6:7], 0, v[4:5]
	v_lshl_add_u64 v[6:7], s[8:9], 0, v[48:49]
	v_lshl_add_u64 v[6:7], v[6:7], 0, s[92:93]
	v_lshl_add_u64 v[12:13], v[6:7], 0, v[4:5]
	v_lshlrev_b32_e32 v4, 4, v169
	v_add3_u32 v172, 0, v171, v4
	v_or_b32_e32 v4, 32, v55
	v_cmp_lt_u32_e64 s[8:9], v4, v3
	v_or_b32_e32 v4, 33, v55
	v_cmp_lt_u32_e64 s[12:13], v4, v3
	v_or_b32_e32 v4, 34, v55
	v_cmp_lt_u32_e64 s[16:17], v4, v3
	v_or_b32_e32 v4, 35, v55
	v_cmp_lt_u32_e64 s[20:21], v4, v3
	v_or_b32_e32 v4, 40, v55
	v_cmp_lt_u32_e64 s[24:25], v4, v3
	v_or_b32_e32 v4, 41, v55
	v_cmp_lt_u32_e64 s[28:29], v4, v3
	v_or_b32_e32 v4, 42, v55
	v_cmp_lt_u32_e64 s[34:35], v4, v3
	v_or_b32_e32 v4, 43, v55
	v_cmp_lt_u32_e64 s[38:39], v4, v3
	v_or_b32_e32 v4, 48, v55
	v_cmp_lt_u32_e64 s[42:43], v4, v3
	v_or_b32_e32 v4, 49, v55
	v_cmp_lt_u32_e64 s[46:47], v4, v3
	v_or_b32_e32 v4, 50, v55
	v_cmp_lt_u32_e64 s[50:51], v4, v3
	v_or_b32_e32 v4, 51, v55
	v_lshlrev_b32_e32 v6, 16, v32
	v_and_b32_e32 v7, 0xffff0000, v32
	v_lshlrev_b32_e32 v8, 16, v33
	v_and_b32_e32 v9, 0xffff0000, v33
	v_cmp_lt_u32_e64 s[54:55], v4, v3
	v_or_b32_e32 v4, 56, v55
	global_store_dwordx4 v[10:11], v[6:9], off
	v_cmp_lt_u32_e64 s[58:59], v4, v3
	v_or_b32_e32 v4, 57, v55
	v_lshlrev_b32_e32 v6, 16, v34
	v_and_b32_e32 v7, 0xffff0000, v34
	v_lshlrev_b32_e32 v8, 16, v35
	v_and_b32_e32 v9, 0xffff0000, v35
	global_store_dwordx4 v[10:11], v[6:9], off offset:128
	v_cmp_lt_u32_e64 s[62:63], v4, v3
	v_or_b32_e32 v4, 58, v55
	v_lshlrev_b32_e32 v6, 16, v36
	v_and_b32_e32 v7, 0xffff0000, v36
	v_lshlrev_b32_e32 v8, 16, v37
	v_and_b32_e32 v9, 0xffff0000, v37
	global_store_dwordx4 v[12:13], v[6:9], off
	v_cmp_lt_u32_e64 s[66:67], v4, v3
	v_or_b32_e32 v4, 59, v55
	v_lshlrev_b32_e32 v6, 16, v38
	v_and_b32_e32 v7, 0xffff0000, v38
	v_lshlrev_b32_e32 v8, 16, v39
	v_and_b32_e32 v9, 0xffff0000, v39
	global_store_dwordx4 v[12:13], v[6:9], off offset:128
	v_cmp_lt_u32_e64 s[6:7], v55, v3
	v_cmp_lt_u32_e64 s[70:71], v4, v3
	s_lshl_b32 s3, s3, 2
	v_mov_b32_e32 v2, v5
	v_mov_b32_e32 v3, v5
	v_mov_b32_e32 v4, v5
	v_mov_b32_e32 v6, v5
	v_mov_b32_e32 v7, v5
	v_mov_b32_e32 v8, v5
	v_mov_b32_e32 v9, v5
	v_mov_b32_e32 v10, v5
	v_mov_b32_e32 v11, v5
	v_mov_b32_e32 v12, v5
	v_mov_b32_e32 v13, v5
	v_mov_b32_e32 v14, v5
	v_mov_b32_e32 v15, v5
	v_lshlrev_b32_e32 v173, 2, v20
	v_mov_b64_e32 v[34:35], v[16:17]
	v_mov_b64_e32 v[50:51], v[16:17]
	s_add_i32 s1, s1, 0x20c00
	s_mov_b32 s85, 0
	s_lshl_b32 s93, s4, 13
	s_sub_i32 s94, 0x30000, s5
	s_sub_i32 s95, s4, s3
	s_sub_i32 s33, 0, s3
	v_mov_b32_e32 v52, 0
	s_mov_b64 s[74:75], 0
	v_mov_b64_e32 v[32:33], v[14:15]
	v_mov_b64_e32 v[30:31], v[12:13]
	v_mov_b64_e32 v[28:29], v[10:11]
	v_mov_b64_e32 v[26:27], v[8:9]
	v_mov_b64_e32 v[24:25], v[6:7]
	v_mov_b64_e32 v[22:23], v[4:5]
	v_mov_b64_e32 v[20:21], v[2:3]
	v_mov_b64_e32 v[48:49], v[14:15]
	v_mov_b64_e32 v[46:47], v[12:13]
	v_mov_b64_e32 v[44:45], v[10:11]
	v_mov_b64_e32 v[42:43], v[8:9]
	v_mov_b64_e32 v[40:41], v[6:7]
	v_mov_b64_e32 v[38:39], v[4:5]
	v_mov_b64_e32 v[36:37], v[2:3]
	s_mov_b32 s3, 28
	s_add_i32 s89, s33, s3
	s_waitcnt lgkmcnt(0)
	s_barrier
	s_branch .LBB0_281

; #define LAS __attribute__((address_space(3)))
; __device__ __forceinline__ void conv_load(ConvRegs& c, const Args& a, size_t rowq, int col, int lane) {
; #pragma unroll
;     for (int i = 0; i < 4; ++i) { const size_t grow = rowq + i * 8 + (lane >> 3);
; __device__ __forceinline__ void prompt_unit_fox(const Args& a, int l, int b, int h, int qb, LAS unsigned char* lds) {
;     int tid_ = threadIdx.x; asm volatile("" : "+v"(tid_));
;     const int tid = tid_, lane = tid & 63, r32 = lane & 31, hi = lane >> 5, wid = __builtin_amdgcn_readfirstlane(tid >> 6);
;     const int q0 = qb * 256, NP = (q0 + 256) / 128, jd = q0 / 64 + (wid >> 1), jpd = jd >> 1;
;     const bool lateB = wid >= 4;
;     const int col = h * HD;
;     const size_t rowb = (size_t)b * T;
;     const bf16* Kh = (const bf16*)(a.ws + WS_K) + rowb * D + col; const bf16* Vh = (const bf16*)(a.ws + WS_V) + rowb * D + col;
;     const unsigned lds0 = (unsigned)(uintptr_t)lds;
;     const bf16* ksrc = Kh + (size_t)lane * D + wid * 8;
;     const bf16* vsrc = Vh + (size_t)(16 * (wid & 3) + (lane >> 2)) * D + (wid >> 2) * 32 + (lane & 3) * 8;
;     ...
;     ATT_DMA2(NP - 1, 0);
;     { const int idx = tid * 4; if (idx < q0 + 256) { const f32x4 c = *(const f32x4*)((const float*)(a.ws + WS_CKP) + (size_t)(b * 8 + h) * T + idx); *(LAS f32x4*)(lds + F_CK + idx * 4) = c;
; #pragma unroll
;         for (int e = 0; e < 4; ++e) { const float h1 = bf_hi_part(c[e]), r1 = c[e] - h1, h2 = bf_hi_part(r1), r2 = r1 - h2; ((LAS u32x2*)(lds + F_AUG))[idx + e] = (u32x2){cvtpk(h1, h2), cvtpk(r2, -1.0f)}; } } }
;     bf16x8 qr[4];
;     { const bf16* Qw = (const bf16*)(a.ws + WS_Q) + (rowb + q0 + wid * 32 + r32) * D + col;
; #pragma unroll
;       for (int d0 = 0; d0 < 4; ++d0) qr[d0] = *(const bf16x8*)(Qw + d0 * 16 + hi * 8); }
;     const lds_cptr vp0 = (lds_cptr)lds + F_V + ((lane >> 4) & 1) * 32 + (lane & 3) * 8 + (4 * hi + ((lane & 15) >> 2)) * 64;
;     const int ql = 32 * (wid & 1) + r32, qlim = ql + 1;
;     LAS float* wsf = (LAS float*)(lds + F_WSF) + wid * 64;
;     FoxState st; st.m = 0.f; st.l = 0.f; st.mq = (bf16x8){}; st.o[0] = (f32x16){}; st.o[1] = (f32x16){};
;     PairP pp; bool pending = false;
; #pragma unroll
;     for (int i = 0; i < 8; ++i) pp.w[i] = (u32x4){0u, 0u, 0u, 0u};
;     { ConvRegs cv; conv_load(cv, a, rowb + q0 + wid * 32, col, lane); conv_store<0>(cv, a, l, h, rowb + q0 + wid * 32, lane); }
.LBB0_311:
	s_or_b64 exec, exec, s[0:1]
	s_lshl_b32 s0, s6, 2
	s_ashr_i32 s1, s3, 7
	s_add_i32 s1, s1, s0
	s_ashr_i32 s89, s1, 1
	s_cmp_lt_i32 s77, 4
	s_cselect_b64 s[92:93], -1, 0
	s_lshl_b32 s0, s5, 11
	s_lshl_b32 s5, s77, 5
	s_or_b32 s0, s7, s0
	s_ashr_i32 s1, s5, 31
	s_add_u32 s91, s5, s0
	v_and_b32_e32 v175, 31, v19
	s_addc_u32 s0, s1, 0
	v_or_b32_e32 v168, s91, v175
	v_mov_b32_e32 v169, s0
	v_lshrrev_b32_e32 v1, 3, v20
	v_lshlrev_b64 v[2:3], 11, v[168:169]
	v_or_b32_e32 v168, s91, v1
	v_lshlrev_b32_e32 v4, 3, v20
	v_lshlrev_b64 v[170:171], 11, v[168:169]
	s_lshl_b32 s74, s4, 1
	s_mov_b32 s75, s87
	v_and_b32_e32 v174, 56, v4
	v_lshl_add_u64 v[8:9], s[94:95], 0, v[170:171]
	v_lshl_add_u64 v[8:9], v[8:9], 0, s[74:75]
	v_mov_b32_e32 v4, v174
	v_readlane_b32 s6, v242, 20
	v_lshl_add_u64 v[8:9], v[8:9], 0, v[4:5]
	v_readlane_b32 s7, v242, 21
	global_load_dwordx2 v[24:25], v[8:9], off offset:64
	global_load_dwordx2 v[22:23], v[8:9], off
	v_or_b32_e32 v58, 0x4000, v170
	v_lshl_add_u64 v[8:9], s[6:7], 0, v[170:171]
	v_lshl_add_u64 v[8:9], v[8:9], 0, s[74:75]
	v_lshl_add_u64 v[8:9], v[8:9], 0, v[4:5]
	v_mov_b32_e32 v59, v171
	global_load_dwordx2 v[28:29], v[8:9], off offset:64
	global_load_dwordx2 v[26:27], v[8:9], off
	v_lshl_add_u64 v[8:9], s[94:95], 0, v[58:59]
	v_lshl_add_u64 v[8:9], v[8:9], 0, s[74:75]
	v_lshl_add_u64 v[8:9], v[8:9], 0, v[4:5]
	global_load_dwordx2 v[32:33], v[8:9], off offset:64
	global_load_dwordx2 v[30:31], v[8:9], off
	v_lshl_add_u64 v[8:9], s[6:7], 0, v[58:59]
	v_lshrrev_b32_e32 v21, 5, v20
	v_lshl_add_u64 v[8:9], v[8:9], 0, s[74:75]
	v_lshlrev_b32_e32 v7, 1, v19
	v_lshrrev_b32_e32 v10, 2, v19
	v_lshlrev_b32_e32 v66, 2, v21
	v_lshl_add_u64 v[8:9], v[8:9], 0, v[4:5]
	v_and_b32_e32 v7, 32, v7
	global_load_dwordx2 v[36:37], v[8:9], off offset:64
	global_load_dwordx2 v[34:35], v[8:9], off
	v_and_or_b32 v8, v10, 3, v66
	v_add_u32_e32 v7, 0, v7
	v_lshlrev_b32_e32 v8, 6, v8
	v_or_b32_e32 v60, 0x8000, v170
	v_mov_b32_e32 v61, v171
	v_add3_u32 v180, v7, v6, v8
	v_lshl_add_u64 v[6:7], s[94:95], 0, v[60:61]
	v_and_or_b32 v67, s5, 32, v175
	s_and_b32 s5, s3, 0x3fffffc0
	v_lshl_add_u64 v[6:7], v[6:7], 0, s[74:75]
	v_writelane_b32 v237, s0, 11
	s_lshl_b32 s0, s4, 2
	s_lshl_b32 s4, s5, 2
	v_lshl_add_u64 v[6:7], v[6:7], 0, v[4:5]
	v_lshl_add_u64 v[10:11], s[6:7], 0, v[60:61]
	s_add_i32 s78, s4, 0
	v_readlane_b32 s4, v242, 22
	global_load_dwordx2 v[40:41], v[6:7], off offset:64
	global_load_dwordx2 v[38:39], v[6:7], off
	v_lshl_add_u64 v[10:11], v[10:11], 0, s[74:75]
	v_readlane_b32 s5, v242, 23
	v_lshl_add_u64 v[10:11], v[10:11], 0, v[4:5]
	v_readlane_b32 s8, v242, 45
	v_lshl_add_u64 v[2:3], s[4:5], 0, v[2:3]
	v_readlane_b32 s4, v242, 43
	global_load_dwordx2 v[44:45], v[10:11], off offset:64
	global_load_dwordx2 v[42:43], v[10:11], off
	v_mov_b32_e32 v173, v5
	v_lshlrev_b32_e32 v172, 4, v21
	v_lshl_add_u64 v[2:3], v[2:3], 0, s[74:75]
	v_or_b32_e32 v62, 0xc000, v170
	v_mov_b32_e32 v63, v171
	v_readlane_b32 s5, v242, 44
	v_readlane_b32 s9, v242, 46
	s_mov_b32 s1, s87
	v_lshl_add_u64 v[6:7], s[4:5], 0, v[170:171]
	v_lshl_add_u64 v[8:9], s[8:9], 0, v[170:171]
	v_lshl_add_u64 v[2:3], v[2:3], 0, v[172:173]
	v_lshl_add_u64 v[46:47], s[94:95], 0, v[62:63]
	v_lshl_add_u64 v[48:49], s[6:7], 0, v[62:63]
	v_lshl_add_u64 v[54:55], v[6:7], 0, s[0:1]
	v_lshl_add_u64 v[56:57], v[8:9], 0, s[0:1]
	global_load_dwordx4 v[6:9], v[2:3], off
	global_load_dwordx4 v[10:13], v[2:3], off offset:32
	global_load_dwordx4 v[14:17], v[2:3], off offset:64
	global_load_dwordx4 v[116:119], v[2:3], off offset:96
	v_lshl_add_u64 v[2:3], v[46:47], 0, s[74:75]
	v_lshl_add_u64 v[46:47], v[48:49], 0, s[74:75]
	v_lshl_add_u64 v[2:3], v[2:3], 0, v[4:5]
	v_lshl_add_u64 v[50:51], v[46:47], 0, v[4:5]
	global_load_dwordx2 v[48:49], v[2:3], off offset:64
	global_load_dwordx2 v[46:47], v[2:3], off
	s_nop 0
	global_load_dwordx2 v[52:53], v[50:51], off offset:64
	global_load_dwordx2 v[50:51], v[50:51], off
	v_lshlrev_b32_e32 v4, 1, v174
	v_lshl_add_u64 v[2:3], v[54:55], 0, v[4:5]
	v_lshl_add_u64 v[64:65], v[56:57], 0, v[4:5]
	s_add_i32 s78, s78, 0x1a000
	v_cmp_lt_u32_e64 s[12:13], v66, v67
	v_cmp_gt_u32_e64 s[6:7], 32, v20
	v_lshlrev_b32_e32 v173, 10, v21
	v_lshlrev_b32_e32 v188, 4, v175
	v_cndmask_b32_e64 v122, 0, v185, s[6:7]
	v_cndmask_b32_e64 v121, 0, -1.0, s[6:7]
	v_mov_b32_e32 v120, v5
	v_mov_b32_e32 v123, v5
	v_lshl_add_u32 v182, v175, 2, s78
	v_mov_b32_e32 v156, v5
	s_waitcnt vmcnt(0)
; __device__ __forceinline__ float bflo(unsigned w) { return __uint_as_float(w << 16); }
; __device__ __forceinline__ float bfhi(unsigned w) { return __uint_as_float(w & 0xffff0000u); }
; template <int TYPE>
; __device__ __forceinline__ void conv_store(const ConvRegs& c, const Args& a, int l, int h, size_t rowq, int lane) {
; #pragma unroll
;     for (int i = 0; i < 4; ++i) { const size_t grow = rowq + i * 8 + (lane >> 3);
;         float* ko = a.out + (TYPE == 0 ? O_FKP : O_SKP) + ((size_t)l * MP + grow) * W + h * HD + (lane & 7) * 8;
;         float* vo = a.out + (TYPE == 0 ? O_FVP : O_SVP) + ((size_t)l * MP + grow) * W + h * HD + (lane & 7) * 8;
;         const u32x4 kw = c.k[i], vw = c.v[i];
;         __builtin_nontemporal_store((f32x4){bflo(kw.x), bfhi(kw.x), bflo(kw.y), bfhi(kw.y)}, (f32x4*)ko); __builtin_nontemporal_store((f32x4){bflo(kw.z), bfhi(kw.z), bflo(kw.w), bfhi(kw.w)}, (f32x4*)(ko + 4));
;         __builtin_nontemporal_store((f32x4){bflo(vw.x), bfhi(vw.x), bflo(vw.y), bfhi(vw.y)}, (f32x4*)vo); __builtin_nontemporal_store((f32x4){bflo(vw.z), bfhi(vw.z), bflo(vw.w), bfhi(vw.w)}, (f32x4*)(vo + 4)); }
; }
	v_lshlrev_b32_e32 v54, 16, v22
	v_and_b32_e32 v55, 0xffff0000, v22
	v_lshlrev_b32_e32 v56, 16, v23
	v_and_b32_e32 v57, 0xffff0000, v23
	v_lshlrev_b32_e32 v22, 16, v24
	v_and_b32_e32 v23, 0xffff0000, v24
	v_lshlrev_b32_e32 v24, 16, v25
	v_and_b32_e32 v25, 0xffff0000, v25
	global_store_dwordx4 v[2:3], v[22:25], off offset:128
	global_store_dwordx4 v[2:3], v[54:57], off
	v_lshl_add_u64 v[2:3], s[4:5], 0, v[58:59]
	v_lshlrev_b32_e32 v22, 16, v26
	v_and_b32_e32 v23, 0xffff0000, v26
	v_lshlrev_b32_e32 v24, 16, v27
	v_and_b32_e32 v25, 0xffff0000, v27
	global_store_dwordx4 v[64:65], v[22:25], off
	v_lshl_add_u64 v[2:3], v[2:3], 0, s[0:1]
	v_lshl_add_u64 v[2:3], v[2:3], 0, v[4:5]
	v_lshlrev_b32_e32 v22, 16, v28
	v_and_b32_e32 v23, 0xffff0000, v28
	v_lshlrev_b32_e32 v24, 16, v29
	v_and_b32_e32 v25, 0xffff0000, v29
	global_store_dwordx4 v[64:65], v[22:25], off offset:128
	v_mov_b32_e32 v54, v5
	v_mov_b32_e32 v55, v5
	v_lshl_add_u64 v[22:23], s[8:9], 0, v[58:59]
	v_lshl_add_u64 v[22:23], v[22:23], 0, s[0:1]
	v_lshl_add_u64 v[26:27], v[22:23], 0, v[4:5]
	v_lshlrev_b32_e32 v22, 16, v30
	v_and_b32_e32 v23, 0xffff0000, v30
	v_lshlrev_b32_e32 v24, 16, v31
	v_and_b32_e32 v25, 0xffff0000, v31
	global_store_dwordx4 v[2:3], v[22:25], off
	v_mov_b32_e32 v56, v5
	v_mov_b32_e32 v57, v5
	v_lshlrev_b32_e32 v22, 16, v32
	v_and_b32_e32 v23, 0xffff0000, v32
	v_lshlrev_b32_e32 v24, 16, v33
	v_and_b32_e32 v25, 0xffff0000, v33
	global_store_dwordx4 v[2:3], v[22:25], off offset:128
	v_lshl_add_u64 v[2:3], s[4:5], 0, v[60:61]
	v_lshl_add_u64 v[2:3], v[2:3], 0, s[0:1]
	v_lshlrev_b32_e32 v22, 16, v34
	v_and_b32_e32 v23, 0xffff0000, v34
	v_lshlrev_b32_e32 v24, 16, v35
	v_and_b32_e32 v25, 0xffff0000, v35
	global_store_dwordx4 v[26:27], v[22:25], off
	v_lshl_add_u64 v[2:3], v[2:3], 0, v[4:5]
	v_mov_b32_e32 v58, v5
	v_lshlrev_b32_e32 v22, 16, v36
	v_and_b32_e32 v23, 0xffff0000, v36
	v_lshlrev_b32_e32 v24, 16, v37
	v_and_b32_e32 v25, 0xffff0000, v37
	global_store_dwordx4 v[26:27], v[22:25], off offset:128
	v_mov_b32_e32 v59, v5
	v_mov_b32_e32 v64, v5
	v_lshl_add_u64 v[22:23], s[8:9], 0, v[60:61]
	v_lshl_add_u64 v[22:23], v[22:23], 0, s[0:1]
	v_lshl_add_u64 v[26:27], v[22:23], 0, v[4:5]
	v_lshlrev_b32_e32 v22, 16, v38
	v_and_b32_e32 v23, 0xffff0000, v38
	v_lshlrev_b32_e32 v24, 16, v39
	v_and_b32_e32 v25, 0xffff0000, v39
	global_store_dwordx4 v[2:3], v[22:25], off
	v_mov_b32_e32 v60, v5
	v_mov_b32_e32 v61, v5
	v_lshlrev_b32_e32 v22, 16, v40
	v_and_b32_e32 v23, 0xffff0000, v40
	v_lshlrev_b32_e32 v24, 16, v41
	v_and_b32_e32 v25, 0xffff0000, v41
	global_store_dwordx4 v[2:3], v[22:25], off offset:128
	v_lshl_add_u64 v[2:3], s[4:5], 0, v[62:63]
	v_lshl_add_u64 v[2:3], v[2:3], 0, s[0:1]
	v_lshlrev_b32_e32 v22, 16, v42
	v_and_b32_e32 v23, 0xffff0000, v42
	v_lshlrev_b32_e32 v24, 16, v43
	v_and_b32_e32 v25, 0xffff0000, v43
	global_store_dwordx4 v[26:27], v[22:25], off
	v_lshl_add_u64 v[2:3], v[2:3], 0, v[4:5]
	v_mov_b32_e32 v65, v5
	v_lshlrev_b32_e32 v22, 16, v44
	v_and_b32_e32 v23, 0xffff0000, v44
	v_lshlrev_b32_e32 v24, 16, v45
	v_and_b32_e32 v25, 0xffff0000, v45
	global_store_dwordx4 v[26:27], v[22:25], off offset:128
	v_mov_b32_e32 v157, v5
	v_mov_b32_e32 v158, v5
	v_lshl_add_u64 v[22:23], s[8:9], 0, v[62:63]
	v_lshl_add_u64 v[22:23], v[22:23], 0, s[0:1]
	v_lshl_add_u64 v[26:27], v[22:23], 0, v[4:5]
	v_lshlrev_b32_e32 v22, 16, v46
	v_and_b32_e32 v23, 0xffff0000, v46
	v_lshlrev_b32_e32 v24, 16, v47
	v_and_b32_e32 v25, 0xffff0000, v47
	global_store_dwordx4 v[2:3], v[22:25], off
	s_add_i32 s1, 0, 0x18000
	v_add_u32_e32 v184, s1, v172
	v_lshlrev_b32_e32 v22, 16, v48
	v_and_b32_e32 v23, 0xffff0000, v48
	v_lshlrev_b32_e32 v24, 16, v49
	v_and_b32_e32 v25, 0xffff0000, v49
	global_store_dwordx4 v[2:3], v[22:25], off offset:128
; #define LAS __attribute__((address_space(3)))
; __device__ __forceinline__ float bflo(unsigned w) { return __uint_as_float(w << 16); }
; __device__ __forceinline__ float bfhi(unsigned w) { return __uint_as_float(w & 0xffff0000u); }
; #define ATT_WAIT_BAR() asm volatile("s_waitcnt vmcnt(0) lgkmcnt(0)\n\ts_barrier" ::: "memory")
; template <int TYPE>
; __device__ __forceinline__ void conv_store(const ConvRegs& c, const Args& a, int l, int h, size_t rowq, int lane) {
; #pragma unroll
;     for (int i = 0; i < 4; ++i) { const size_t grow = rowq + i * 8 + (lane >> 3);
;         float* ko = a.out + (TYPE == 0 ? O_FKP : O_SKP) + ((size_t)l * MP + grow) * W + h * HD + (lane & 7) * 8;
;         float* vo = a.out + (TYPE == 0 ? O_FVP : O_SVP) + ((size_t)l * MP + grow) * W + h * HD + (lane & 7) * 8;
;         const u32x4 kw = c.k[i], vw = c.v[i];
;         __builtin_nontemporal_store((f32x4){bflo(kw.x), bfhi(kw.x), bflo(kw.y), bfhi(kw.y)}, (f32x4*)ko); __builtin_nontemporal_store((f32x4){bflo(kw.z), bfhi(kw.z), bflo(kw.w), bfhi(kw.w)}, (f32x4*)(ko + 4));
;         __builtin_nontemporal_store((f32x4){bflo(vw.x), bfhi(vw.x), bflo(vw.y), bfhi(vw.y)}, (f32x4*)vo); __builtin_nontemporal_store((f32x4){bflo(vw.z), bfhi(vw.z), bflo(vw.w), bfhi(vw.w)}, (f32x4*)(vo + 4)); }
; }
; __device__ __forceinline__ void prompt_unit_fox(const Args& a, int l, int b, int h, int qb, LAS unsigned char* lds) {
;     ...
;     const lds_cptr vp0 = (lds_cptr)lds + F_V + ((lane >> 4) & 1) * 32 + (lane & 3) * 8 + (4 * hi + ((lane & 15) >> 2)) * 64;
;     const int ql = 32 * (wid & 1) + r32, qlim = ql + 1;
;     LAS float* wsf = (LAS float*)(lds + F_WSF) + wid * 64;
;     FoxState st; st.m = 0.f; st.l = 0.f; st.mq = (bf16x8){}; st.o[0] = (f32x16){}; st.o[1] = (f32x16){};
;     PairP pp; bool pending = false;
; #pragma unroll
;     for (int i = 0; i < 8; ++i) pp.w[i] = (u32x4){0u, 0u, 0u, 0u};
;     { ConvRegs cv; conv_load(cv, a, rowb + q0 + wid * 32, col, lane); conv_store<0>(cv, a, l, h, rowb + q0 + wid * 32, lane); }
;     int slot = 0, pslot = 0;
;     ...
;         ATT_WAIT_BAR();
	v_or_b32_e32 v2, 32, v66
	v_cmp_gt_u32_e64 s[10:11], v2, v67
	v_or_b32_e32 v2, 33, v66
	v_cmp_gt_u32_e64 s[14:15], v2, v67
	v_or_b32_e32 v2, 2, v66
	v_cmp_gt_u32_e64 s[16:17], v2, v67
	v_or_b32_e32 v2, 34, v66
	v_cmp_gt_u32_e64 s[18:19], v2, v67
	v_or_b32_e32 v2, 3, v66
	v_cmp_gt_u32_e64 s[20:21], v2, v67
	v_or_b32_e32 v2, 35, v66
	v_cmp_gt_u32_e64 s[22:23], v2, v67
	v_or_b32_e32 v2, 8, v66
	v_cmp_gt_u32_e64 s[24:25], v2, v67
	v_or_b32_e32 v2, 40, v66
	v_cmp_gt_u32_e64 s[26:27], v2, v67
	v_or_b32_e32 v2, 9, v66
	v_cmp_gt_u32_e64 s[28:29], v2, v67
	v_or_b32_e32 v2, 41, v66
	v_cmp_gt_u32_e64 s[30:31], v2, v67
	v_or_b32_e32 v2, 10, v66
	v_cmp_gt_u32_e64 s[34:35], v2, v67
	v_or_b32_e32 v2, 42, v66
	v_cmp_gt_u32_e64 s[36:37], v2, v67
	v_or_b32_e32 v2, 11, v66
	v_cmp_gt_u32_e64 s[38:39], v2, v67
	v_or_b32_e32 v2, 43, v66
	v_cmp_gt_u32_e64 s[40:41], v2, v67
	v_or_b32_e32 v2, 16, v66
	v_cmp_gt_u32_e64 s[42:43], v2, v67
	v_or_b32_e32 v2, 48, v66
	v_cmp_gt_u32_e64 s[44:45], v2, v67
	v_or_b32_e32 v2, 17, v66
	v_cmp_gt_u32_e64 s[46:47], v2, v67
	v_or_b32_e32 v2, 49, v66
	v_cmp_gt_u32_e64 s[48:49], v2, v67
	v_or_b32_e32 v2, 18, v66
	v_cmp_gt_u32_e64 s[50:51], v2, v67
	v_or_b32_e32 v2, 50, v66
	v_cmp_gt_u32_e64 s[52:53], v2, v67
	v_or_b32_e32 v2, 19, v66
	v_cmp_gt_u32_e64 s[54:55], v2, v67
	v_or_b32_e32 v2, 51, v66
	v_cmp_gt_u32_e64 s[56:57], v2, v67
	v_or_b32_e32 v2, 24, v66
	v_cmp_gt_u32_e64 s[58:59], v2, v67
	v_or_b32_e32 v2, 56, v66
	v_cmp_gt_u32_e64 s[60:61], v2, v67
	v_or_b32_e32 v2, 25, v66
	v_cmp_gt_u32_e64 s[62:63], v2, v67
	v_or_b32_e32 v2, 57, v66
	v_cmp_gt_u32_e64 s[64:65], v2, v67
	v_or_b32_e32 v2, 26, v66
	v_cmp_gt_u32_e64 s[66:67], v2, v67
	v_or_b32_e32 v2, 58, v66
	v_cmp_gt_u32_e64 s[68:69], v2, v67
	v_or_b32_e32 v2, 27, v66
	v_cmp_gt_u32_e64 s[70:71], v2, v67
	v_or_b32_e32 v2, 59, v66
	v_lshlrev_b32_e32 v22, 16, v50
	v_and_b32_e32 v23, 0xffff0000, v50
	v_lshlrev_b32_e32 v24, 16, v51
	v_and_b32_e32 v25, 0xffff0000, v51
	s_add_i32 s1, 0, 0x1a800
	v_cmp_gt_u32_e64 s[8:9], v66, v67
	v_cmp_gt_u32_e64 s[72:73], v2, v67
	v_mov_b32_e32 v66, v5
	v_mov_b32_e32 v67, v5
	global_store_dwordx4 v[26:27], v[22:25], off
	s_bitcmp1_b32 s3, 7
	v_mov_b32_e32 v62, v5
	v_lshlrev_b32_e32 v22, 16, v52
	v_and_b32_e32 v23, 0xffff0000, v52
	v_lshlrev_b32_e32 v24, 16, v53
	v_and_b32_e32 v25, 0xffff0000, v53
	v_mov_b32_e32 v52, v5
	v_mov_b32_e32 v53, v5
	v_mov_b32_e32 v63, v5
	v_mov_b64_e32 v[82:83], v[66:67]
	v_lshl_add_u32 v186, v175, 3, s1
	s_cselect_b64 s[94:95], -1, 0
	s_mov_b32 s1, 0
	v_mov_b32_e32 v159, v5
	v_mov_b32_e32 v192, 0
	v_mov_b32_e32 v124, 0
	v_mov_b32_e32 v125, 0
	v_mov_b32_e32 v126, 0
	v_mov_b32_e32 v127, 0
	v_mov_b32_e32 v128, 0
	v_mov_b32_e32 v129, 0
	v_mov_b32_e32 v130, 0
	v_mov_b32_e32 v131, 0
	v_mov_b32_e32 v132, 0
	v_mov_b32_e32 v133, 0
	v_mov_b32_e32 v134, 0
	v_mov_b32_e32 v135, 0
	v_mov_b32_e32 v136, 0
	v_mov_b32_e32 v137, 0
	v_mov_b32_e32 v138, 0
	v_mov_b32_e32 v139, 0
	v_mov_b32_e32 v140, 0
	v_mov_b32_e32 v141, 0
	v_mov_b32_e32 v142, 0
	v_mov_b32_e32 v143, 0
	v_mov_b32_e32 v144, 0
	v_mov_b32_e32 v145, 0
	v_mov_b32_e32 v146, 0
	v_mov_b32_e32 v147, 0
	v_mov_b32_e32 v148, 0
	v_mov_b32_e32 v149, 0
	v_mov_b32_e32 v150, 0
	v_mov_b32_e32 v151, 0
	v_mov_b32_e32 v152, 0
	v_mov_b32_e32 v153, 0
	v_mov_b32_e32 v154, 0
	v_mov_b32_e32 v155, 0
	v_cndmask_b32_e64 v2, 0, v187, s[6:7]
	s_mov_b32 s75, 0
	v_mov_b64_e32 v[80:81], v[64:65]
	v_mov_b64_e32 v[78:79], v[62:63]
	v_mov_b64_e32 v[76:77], v[60:61]
	v_mov_b64_e32 v[74:75], v[58:59]
	v_mov_b64_e32 v[72:73], v[56:57]
	v_mov_b64_e32 v[70:71], v[54:55]
	v_mov_b64_e32 v[68:69], v[52:53]
	v_mov_b32_e32 v193, 0
	s_mov_b64 s[4:5], 0
	global_store_dwordx4 v[26:27], v[22:25], off offset:128
	s_waitcnt vmcnt(16) lgkmcnt(0)
	s_barrier
	s_branch .Lfox_top_l0

; #define LAS __attribute__((address_space(3)))
; #define ATT_DMA(jt, slot) do { glds16(ksrc + (size_t)(jt) * 64 * D, (unsigned)__builtin_amdgcn_readfirstlane(lds0 + A_K + (slot) * 8192 + wid * 1024)); \
;                                glds16(vsrc + (size_t)(jt) * 64 * D, (unsigned)__builtin_amdgcn_readfirstlane(lds0 + A_V + (slot) * 8192 + wid * 1024)); } while (0)
; __device__ __forceinline__ void conv_load(ConvRegs& c, const Args& a, size_t rowq, int col, int lane) {
; #pragma unroll
;     for (int i = 0; i < 4; ++i) { const size_t grow = rowq + i * 8 + (lane >> 3);
;         c.k[i] = *(const u32x4*)((const bf16*)(a.ws + WS_K) + grow * D + col + (lane & 7) * 8); c.v[i] = *(const u32x4*)((const bf16*)(a.ws + WS_V) + grow * D + col + (lane & 7) * 8); }
; __device__ __forceinline__ void prompt_unit_sb(const Args& a, int l, int b, int h, int qb, LAS unsigned char* lds) {
;     ...
;     f16x8 T00, T01; make_tri(T00, T01, r32, hi);
;     const int q0 = qb * 256, jb = q0 / 64, jd = jb + (wid >> 1);
;     const int col = W + h * HD;
;     const size_t rowb = (size_t)b * T;
;     const bf16* Kh = (const bf16*)(a.ws + WS_K) + rowb * D + col; const bf16* Vh = (const bf16*)(a.ws + WS_V) + rowb * D + col;
;     const unsigned lds0 = (unsigned)(uintptr_t)lds;
;     const bf16* ksrc = Kh + (size_t)lane * D + wid * 8;
;     const bf16* vsrc = Vh + (size_t)(16 * (wid & 3) + (lane >> 2)) * D + (wid >> 2) * 32 + (lane & 3) * 8;
;     ...
;     ATT_DMA(jb + 3); ATT_DMA(jb + 2); ATT_DMA(jb + 1); ATT_DMA(jb);
;     if (jb >= 4) { ATT_DMA(jb - 1); ATT_DMA(jb - 2); ATT_DMA(jb - 3); }
;     bf16x8 qr[4];
;     { const bf16* Qw = (const bf16*)(a.ws + WS_Q) + (rowb + q0 + wid * 32 + r32) * D + col;
; #pragma unroll
;       for (int d0 = 0; d0 < 4; ++d0) qr[d0] = *(const bf16x8*)(Qw + d0 * 16 + hi * 8); }
;     const lds_cptr vp0 = (lds_cptr)lds + B_V + ((lane >> 4) & 1) * 32 + (lane & 3) * 8 + (4 * hi + ((lane & 15) >> 2)) * 64;
;     const int qlim = 32 * (wid & 1) + r32;
;     LAS float* wsf = (LAS float*)(lds + B_WSF) + wid * 64;
;     LAS unsigned* flags = (LAS unsigned*)(lds + B_FLAG);
;     FoxState st; st.m = 0.f; st.l = 0.f; st.mq = (bf16x8){}; st.o[0] = (f32x16){}; st.o[1] = (f32x16){};
;     float R = 0.f; bool done = false;
;     { ConvRegs cv; conv_load(cv, a, rowb + q0 + wid * 32, col, lane); conv_store<1>(cv, a, l, h, rowb + q0 + wid * 32, lane); }
.LBB0_928:
	v_lshrrev_b32_e32 v46, 5, v53
	v_and_b32_e32 v169, 31, v19
	v_lshlrev_b32_e32 v47, 2, v46
	v_cmp_lt_u32_e32 vcc, v47, v169
	v_or_b32_e32 v48, 16, v47
	v_or_b32_e32 v50, 1, v47
	v_cndmask_b32_e64 v3, v179, 0, vcc
	v_cmp_lt_u32_e32 vcc, v48, v169
	v_or_b32_e32 v49, 2, v47
	s_lshl_b32 s3, s7, 8
	v_cndmask_b32_e64 v24, v179, 0, vcc
	v_cmp_lt_u32_e32 vcc, v50, v169
	v_or_b32_e32 v52, 17, v47
	s_ashr_i32 s2, s8, 7
	v_cndmask_b32_e64 v14, v179, 0, vcc
	v_cmp_lt_u32_e32 vcc, v49, v169
	s_ashr_i32 s7, s3, 31
	v_or_b32_e32 v51, 18, v47
	v_cndmask_b32_e64 v15, v179, 0, vcc
	v_cmp_lt_u32_e32 vcc, v52, v169
	s_add_u32 s3, s3, s9
	v_or_b32_e32 v55, 3, v47
	v_cndmask_b32_e64 v25, v179, 0, vcc
	v_cmp_lt_u32_e32 vcc, v51, v169
	s_addc_u32 s7, s7, 0
	s_lshl_b32 s8, s84, 5
	v_cndmask_b32_e64 v26, v179, 0, vcc
	v_or_b32_e32 v54, 8, v47
	v_cmp_lt_u32_e32 vcc, v55, v169
	s_ashr_i32 s9, s8, 31
	v_or_b32_e32 v57, 19, v47
	v_cndmask_b32_e64 v16, v179, 0, vcc
	v_cmp_lt_u32_e32 vcc, v54, v169
	s_add_u32 s82, s3, s8
	v_or_b32_e32 v56, 24, v47
	v_cndmask_b32_e64 v17, v179, 0, vcc
	v_cmp_lt_u32_e32 vcc, v57, v169
	s_addc_u32 s83, s7, s9
	v_or_b32_e32 v58, 10, v47
	v_cndmask_b32_e64 v27, v179, 0, vcc
	v_cmp_lt_u32_e32 vcc, v56, v169
	v_or_b32_e32 v160, s82, v169
	v_mov_b32_e32 v161, s83
	v_readlane_b32 s10, v242, 28
	v_cndmask_b32_e64 v28, v179, 0, vcc
	v_or_b32_e32 v59, 9, v47
	v_cmp_lt_u32_e32 vcc, v58, v169
	v_lshlrev_b64 v[6:7], 11, v[160:161]
	v_readlane_b32 s11, v242, 29
	v_cndmask_b32_e64 v22, v179, 0, vcc
	v_cmp_lt_u32_e32 vcc, v59, v169
	v_or_b32_e32 v60, 26, v47
	v_lshl_add_u64 v[6:7], s[10:11], 0, v[6:7]
	s_lshl_b32 s78, s6, 1
	s_mov_b32 s79, s87
	v_lshrrev_b32_e32 v1, 3, v53
	v_cndmask_b32_e64 v23, v179, 0, vcc
	v_or_b32_e32 v61, 25, v47
	v_lshl_add_u64 v[6:7], v[6:7], 0, s[78:79]
	v_lshlrev_b32_e32 v4, 4, v46
	v_or_b32_e32 v160, s82, v1
	v_readlane_b32 s10, v242, 20
	v_cmp_lt_u32_e32 vcc, v60, v169
	v_lshl_add_u64 v[20:21], v[6:7], 0, v[4:5]
	v_lshlrev_b32_e32 v4, 3, v53
	v_lshlrev_b64 v[162:163], 11, v[160:161]
	v_readlane_b32 s11, v242, 21
	v_cndmask_b32_e64 v29, v179, 0, vcc
	v_cmp_lt_u32_e32 vcc, v61, v169
	v_or_b32_e32 v62, 11, v47
	v_readlane_b32 s12, v242, 22
	v_and_b32_e32 v168, 56, v4
	v_lshl_add_u64 v[6:7], s[10:11], 0, v[162:163]
	v_cndmask_b32_e64 v30, v179, 0, vcc
	v_readlane_b32 s13, v242, 23
	v_cmp_lt_u32_e32 vcc, v62, v169
	v_lshl_add_u64 v[6:7], v[6:7], 0, s[78:79]
	v_mov_b32_e32 v4, v168
	v_lshl_add_u64 v[10:11], s[12:13], 0, v[162:163]
	v_cndmask_b32_e64 v31, v179, 0, vcc
	v_lshl_add_u64 v[6:7], v[6:7], 0, v[4:5]
	v_lshl_add_u64 v[10:11], v[10:11], 0, s[78:79]
	v_pack_b32_f16 v118, v17, v23
	v_pack_b32_f16 v119, v22, v31
	v_or_b32_e32 v63, 27, v47
	v_or_b32_e32 v22, 0x4000, v162
	v_mov_b32_e32 v23, v163
	global_load_dwordx2 v[8:9], v[6:7], off offset:1088
	global_load_dwordx2 v[6:7], v[6:7], off offset:1024
	v_lshl_add_u64 v[10:11], v[10:11], 0, v[4:5]
	v_pack_b32_f16 v117, v15, v16
	v_pack_b32_f16 v116, v3, v14
	v_lshl_add_u64 v[14:15], s[10:11], 0, v[22:23]
	v_cmp_lt_u32_e32 vcc, v63, v169
	global_load_dwordx2 v[12:13], v[10:11], off offset:1088
	global_load_dwordx2 v[10:11], v[10:11], off offset:1024
	v_lshl_add_u64 v[14:15], v[14:15], 0, s[78:79]
	v_cndmask_b32_e64 v3, v179, 0, vcc
	v_lshl_add_u64 v[14:15], v[14:15], 0, v[4:5]
	v_pack_b32_f16 v123, v29, v3
	v_lshlrev_b32_e32 v3, 1, v19
	global_load_dwordx2 v[16:17], v[14:15], off offset:1088
	global_load_dwordx2 v[14:15], v[14:15], off offset:1024
	v_pack_b32_f16 v120, v24, v25
	v_and_b32_e32 v3, 32, v3
	s_add_i32 s3, 0, 0x10000
	v_lshlrev_b32_e32 v24, 4, v19
	global_load_dwordx4 v[124:127], v[20:21], off offset:1024
	global_load_dwordx4 v[128:131], v[20:21], off offset:1056
	global_load_dwordx4 v[132:135], v[20:21], off offset:1088
	global_load_dwordx4 v[136:139], v[20:21], off offset:1120
	v_lshl_add_u64 v[20:21], s[12:13], 0, v[22:23]
	v_add3_u32 v2, s3, v3, v2
	v_lshlrev_b32_e32 v3, 8, v46
	v_and_b32_e32 v24, 0xc0, v24
	v_lshl_add_u64 v[20:21], v[20:21], 0, s[78:79]
	v_add3_u32 v170, v2, v3, v24
	v_or_b32_e32 v2, 0x8000, v162
	v_mov_b32_e32 v3, v163
	v_lshl_add_u64 v[20:21], v[20:21], 0, v[4:5]
	v_lshl_add_u64 v[24:25], s[10:11], 0, v[2:3]
	global_load_dwordx2 v[22:23], v[20:21], off offset:1088
	global_load_dwordx2 v[20:21], v[20:21], off offset:1024
	v_lshl_add_u64 v[24:25], v[24:25], 0, s[78:79]
	v_lshl_add_u64 v[24:25], v[24:25], 0, v[4:5]
	v_lshl_add_u64 v[2:3], s[12:13], 0, v[2:3]
	v_pack_b32_f16 v121, v26, v27
	global_load_dwordx2 v[26:27], v[24:25], off offset:1088
	global_load_dwordx2 v[24:25], v[24:25], off offset:1024
	v_lshl_add_u64 v[2:3], v[2:3], 0, s[78:79]
	v_lshl_add_u64 v[2:3], v[2:3], 0, v[4:5]
	v_pack_b32_f16 v122, v28, v30
	global_load_dwordx2 v[30:31], v[2:3], off offset:1088
	global_load_dwordx2 v[28:29], v[2:3], off offset:1024
	v_or_b32_e32 v2, 0xc000, v162
	v_mov_b32_e32 v3, v163
	v_lshl_add_u64 v[32:33], s[10:11], 0, v[2:3]
	v_lshl_add_u64 v[32:33], v[32:33], 0, s[78:79]
	v_lshl_add_u64 v[2:3], s[12:13], 0, v[2:3]
	v_lshl_add_u64 v[32:33], v[32:33], 0, v[4:5]
	v_lshl_add_u64 v[2:3], v[2:3], 0, s[78:79]
	v_lshl_add_u64 v[2:3], v[2:3], 0, v[4:5]
	global_load_dwordx2 v[34:35], v[32:33], off offset:1088
	global_load_dwordx2 v[32:33], v[32:33], off offset:1024
	s_nop 0
	global_load_dwordx2 v[38:39], v[2:3], off offset:1088
	global_load_dwordx2 v[36:37], v[2:3], off offset:1024
	s_add_u32 s3, s82, 0x10000
	s_addc_u32 s7, s83, 0
	v_and_or_b32 v64, s8, 32, v169
	v_or_b32_e32 v2, s3, v1
	v_mov_b32_e32 v3, s7
	v_readlane_b32 s8, v242, 16
	v_lshlrev_b64 v[2:3], 11, v[2:3]
	v_readlane_b32 s9, v242, 17
	s_lshl_b32 s92, s6, 2
	v_readlane_b32 s6, v242, 24
	v_lshl_add_u64 v[40:41], s[8:9], 0, v[2:3]
	s_mov_b32 s93, s87
	v_readlane_b32 s7, v242, 25
	v_lshl_add_u64 v[40:41], v[40:41], 0, s[92:93]
	v_lshlrev_b32_e32 v4, 1, v168
	v_lshl_add_u64 v[2:3], s[6:7], 0, v[2:3]
	v_lshl_add_u64 v[44:45], v[40:41], 0, v[4:5]
	v_lshl_add_u64 v[2:3], v[2:3], 0, s[92:93]
	v_lshl_add_u64 v[2:3], v[2:3], 0, v[4:5]
	s_movk_i32 s3, 0x4000
	s_mov_b64 s[6:7], 0x4000
	v_lshlrev_b32_e32 v171, 10, v46
	v_cmp_lt_u32_e64 s[10:11], v50, v64
	v_cmp_lt_u32_e64 s[14:15], v49, v64
	v_cmp_lt_u32_e64 s[18:19], v55, v64
	v_cmp_lt_u32_e64 s[22:23], v54, v64
	v_cmp_lt_u32_e64 s[40:41], v48, v64
	v_cmp_lt_u32_e64 s[48:49], v51, v64
	v_or_b32_e32 v54, 58, v47
	v_or_b32_e32 v55, 59, v47
	v_mov_b32_e32 v4, v5
	s_mov_b32 s79, 0
	v_cmp_lt_u32_e64 s[26:27], v59, v64
	s_waitcnt vmcnt(0)
; #define LAS __attribute__((address_space(3)))
; __device__ __forceinline__ float bflo(unsigned w) { return __uint_as_float(w << 16); }
; __device__ __forceinline__ float bfhi(unsigned w) { return __uint_as_float(w & 0xffff0000u); }
; #define ATT_WAIT_BAR_N(N) asm volatile("s_waitcnt vmcnt(" #N ") lgkmcnt(0)\n\ts_barrier" ::: "memory")
; template <int TYPE>
; __device__ __forceinline__ void conv_store(const ConvRegs& c, const Args& a, int l, int h, size_t rowq, int lane) {
; #pragma unroll
;     for (int i = 0; i < 4; ++i) { const size_t grow = rowq + i * 8 + (lane >> 3);
;         float* ko = a.out + (TYPE == 0 ? O_FKP : O_SKP) + ((size_t)l * MP + grow) * W + h * HD + (lane & 7) * 8;
;         float* vo = a.out + (TYPE == 0 ? O_FVP : O_SVP) + ((size_t)l * MP + grow) * W + h * HD + (lane & 7) * 8;
;         const u32x4 kw = c.k[i], vw = c.v[i];
;         __builtin_nontemporal_store((f32x4){bflo(kw.x), bfhi(kw.x), bflo(kw.y), bfhi(kw.y)}, (f32x4*)ko); __builtin_nontemporal_store((f32x4){bflo(kw.z), bfhi(kw.z), bflo(kw.w), bfhi(kw.w)}, (f32x4*)(ko + 4));
;         __builtin_nontemporal_store((f32x4){bflo(vw.x), bfhi(vw.x), bflo(vw.y), bfhi(vw.y)}, (f32x4*)vo); __builtin_nontemporal_store((f32x4){bflo(vw.z), bfhi(vw.z), bflo(vw.w), bfhi(vw.w)}, (f32x4*)(vo + 4)); }
; }
; __device__ __forceinline__ void prompt_unit_sb(const Args& a, int l, int b, int h, int qb, LAS unsigned char* lds) {
;     ...
;     const lds_cptr vp0 = (lds_cptr)lds + B_V + ((lane >> 4) & 1) * 32 + (lane & 3) * 8 + (4 * hi + ((lane & 15) >> 2)) * 64;
;     const int qlim = 32 * (wid & 1) + r32;
;     LAS float* wsf = (LAS float*)(lds + B_WSF) + wid * 64;
;     LAS unsigned* flags = (LAS unsigned*)(lds + B_FLAG);
;     FoxState st; st.m = 0.f; st.l = 0.f; st.mq = (bf16x8){}; st.o[0] = (f32x16){}; st.o[1] = (f32x16){};
;     float R = 0.f; bool done = false;
;     { ConvRegs cv; conv_load(cv, a, rowb + q0 + wid * 32, col, lane); conv_store<1>(cv, a, l, h, rowb + q0 + wid * 32, lane); }
;     for (int it = 0; ; ++it) {
;         const int need = jb - it;
;         if (need >= 3) ATT_WAIT_BAR_N(6); else if (need == 2) ATT_WAIT_BAR_N(4); else if (need == 1) ATT_WAIT_BAR_N(2); else ATT_WAIT_BAR_N(0);
	v_lshlrev_b32_e32 v40, 16, v6
	v_and_b32_e32 v41, 0xffff0000, v6
	v_lshlrev_b32_e32 v42, 16, v7
	v_and_b32_e32 v43, 0xffff0000, v7
	v_lshlrev_b32_e32 v6, 16, v8
	v_and_b32_e32 v7, 0xffff0000, v8
	v_lshlrev_b32_e32 v8, 16, v9
	v_and_b32_e32 v9, 0xffff0000, v9
	global_store_dwordx4 v[44:45], v[6:9], off offset:128
	global_store_dwordx4 v[44:45], v[40:43], off
	v_cmp_lt_u32_e64 s[30:31], v58, v64
	v_lshlrev_b32_e32 v6, 16, v10
	v_and_b32_e32 v7, 0xffff0000, v10
	v_lshlrev_b32_e32 v8, 16, v11
	v_and_b32_e32 v9, 0xffff0000, v11
	global_store_dwordx4 v[2:3], v[6:9], off
	v_lshl_add_u64 v[10:11], v[44:45], 0, s[6:7]
	v_cmp_lt_u32_e64 s[36:37], v62, v64
	v_lshlrev_b32_e32 v6, 16, v12
	v_and_b32_e32 v7, 0xffff0000, v12
	v_lshlrev_b32_e32 v8, 16, v13
	v_and_b32_e32 v9, 0xffff0000, v13
	global_store_dwordx4 v[2:3], v[6:9], off offset:128
	v_lshl_add_u64 v[12:13], v[2:3], 0, s[6:7]
	s_mov_b64 s[6:7], 0x8000
	v_lshlrev_b32_e32 v6, 16, v14
	v_and_b32_e32 v7, 0xffff0000, v14
	v_add_co_u32_e32 v14, vcc, s3, v44
	v_lshlrev_b32_e32 v8, 16, v15
	v_and_b32_e32 v9, 0xffff0000, v15
	v_addc_co_u32_e32 v15, vcc, 0, v45, vcc
	global_store_dwordx4 v[14:15], v[6:9], off
	v_cmp_lt_u32_e64 s[44:45], v52, v64
	v_cmp_lt_u32_e64 s[52:53], v57, v64
	v_lshlrev_b32_e32 v6, 16, v16
	v_and_b32_e32 v7, 0xffff0000, v16
	v_lshlrev_b32_e32 v8, 16, v17
	v_and_b32_e32 v9, 0xffff0000, v17
	global_store_dwordx4 v[10:11], v[6:9], off offset:128
	v_add_co_u32_e32 v10, vcc, s3, v2
	s_nop 0
	v_lshlrev_b32_e32 v6, 16, v20
	v_and_b32_e32 v7, 0xffff0000, v20
	v_lshlrev_b32_e32 v8, 16, v21
	v_and_b32_e32 v9, 0xffff0000, v21
	v_addc_co_u32_e32 v11, vcc, 0, v3, vcc
	s_mov_b32 s3, 0x8000
	global_store_dwordx4 v[10:11], v[6:9], off
	v_add_co_u32_e32 v14, vcc, s3, v44
	s_nop 0
	v_lshlrev_b32_e32 v6, 16, v22
	v_and_b32_e32 v7, 0xffff0000, v22
	v_lshlrev_b32_e32 v8, 16, v23
	v_and_b32_e32 v9, 0xffff0000, v23
	global_store_dwordx4 v[12:13], v[6:9], off offset:128
	v_addc_co_u32_e32 v15, vcc, 0, v45, vcc
	s_nop 0
	v_lshlrev_b32_e32 v6, 16, v24
	v_and_b32_e32 v7, 0xffff0000, v24
	v_lshlrev_b32_e32 v8, 16, v25
	v_and_b32_e32 v9, 0xffff0000, v25
	v_lshl_add_u64 v[10:11], v[44:45], 0, s[6:7]
	global_store_dwordx4 v[14:15], v[6:9], off
	v_lshl_add_u64 v[12:13], v[2:3], 0, s[6:7]
	s_mov_b64 s[6:7], 0xc000
	v_lshlrev_b32_e32 v6, 16, v26
	v_and_b32_e32 v7, 0xffff0000, v26
	v_lshlrev_b32_e32 v8, 16, v27
	v_and_b32_e32 v9, 0xffff0000, v27
	global_store_dwordx4 v[10:11], v[6:9], off offset:128
	v_add_co_u32_e32 v10, vcc, s3, v2
	s_nop 0
	v_lshlrev_b32_e32 v6, 16, v28
	v_and_b32_e32 v7, 0xffff0000, v28
	v_lshlrev_b32_e32 v8, 16, v29
	v_and_b32_e32 v9, 0xffff0000, v29
	v_addc_co_u32_e32 v11, vcc, 0, v3, vcc
	s_mov_b32 s3, 0xc000
	global_store_dwordx4 v[10:11], v[6:9], off
	v_add_co_u32_e32 v14, vcc, s3, v44
	s_nop 0
	v_lshlrev_b32_e32 v6, 16, v30
	v_and_b32_e32 v7, 0xffff0000, v30
	v_lshlrev_b32_e32 v8, 16, v31
	v_and_b32_e32 v9, 0xffff0000, v31
	global_store_dwordx4 v[12:13], v[6:9], off offset:128
	v_addc_co_u32_e32 v15, vcc, 0, v45, vcc
	s_nop 0
	v_lshlrev_b32_e32 v6, 16, v32
	v_and_b32_e32 v7, 0xffff0000, v32
	v_lshlrev_b32_e32 v8, 16, v33
	v_and_b32_e32 v9, 0xffff0000, v33
	v_lshl_add_u64 v[10:11], v[44:45], 0, s[6:7]
	v_lshl_add_u64 v[12:13], v[2:3], 0, s[6:7]
	global_store_dwordx4 v[14:15], v[6:9], off
	v_add_co_u32_e32 v2, vcc, s3, v2
	s_nop 0
	v_lshlrev_b32_e32 v6, 16, v34
	v_and_b32_e32 v7, 0xffff0000, v34
	v_lshlrev_b32_e32 v8, 16, v35
	v_and_b32_e32 v9, 0xffff0000, v35
	global_store_dwordx4 v[10:11], v[6:9], off offset:128
	v_addc_co_u32_e32 v3, vcc, 0, v3, vcc
	s_nop 0
	v_lshlrev_b32_e32 v6, 16, v36
	v_and_b32_e32 v7, 0xffff0000, v36
	v_lshlrev_b32_e32 v8, 16, v37
	v_and_b32_e32 v9, 0xffff0000, v37
	global_store_dwordx4 v[2:3], v[6:9], off
	v_lshlrev_b32_e32 v2, 4, v169
	v_add3_u32 v172, 0, v171, v2
	v_or_b32_e32 v2, 32, v47
	v_cmp_lt_u32_e64 s[8:9], v2, v64
	v_or_b32_e32 v2, 33, v47
	v_cmp_lt_u32_e64 s[12:13], v2, v64
	v_or_b32_e32 v2, 34, v47
	v_cmp_lt_u32_e64 s[16:17], v2, v64
	v_or_b32_e32 v2, 35, v47
	v_cmp_lt_u32_e64 s[20:21], v2, v64
	v_or_b32_e32 v2, 40, v47
	v_cmp_lt_u32_e64 s[24:25], v2, v64
	v_or_b32_e32 v2, 41, v47
	v_cmp_lt_u32_e64 s[28:29], v2, v64
	v_or_b32_e32 v2, 42, v47
	v_cmp_lt_u32_e64 s[34:35], v2, v64
	v_or_b32_e32 v2, 43, v47
	v_cmp_lt_u32_e64 s[38:39], v2, v64
	v_or_b32_e32 v2, 48, v47
	v_cmp_lt_u32_e64 s[42:43], v2, v64
	v_or_b32_e32 v2, 49, v47
	v_cmp_lt_u32_e64 s[46:47], v2, v64
	v_or_b32_e32 v2, 50, v47
	v_cmp_lt_u32_e64 s[50:51], v2, v64
	v_or_b32_e32 v2, 51, v47
	v_cmp_lt_u32_e64 s[54:55], v2, v64
	v_or_b32_e32 v2, 56, v47
	v_lshlrev_b32_e32 v6, 16, v38
	v_and_b32_e32 v7, 0xffff0000, v38
	v_lshlrev_b32_e32 v8, 16, v39
	v_and_b32_e32 v9, 0xffff0000, v39
	s_lshl_b32 s3, s84, 2
	v_cmp_lt_u32_e64 s[58:59], v2, v64
	v_or_b32_e32 v2, 57, v47
	v_mov_b32_e32 v16, v5
	v_mov_b32_e32 v17, v5
	v_and_or_b32 v20, v181, 64, v169
	global_store_dwordx4 v[12:13], v[6:9], off offset:128
	s_add_i32 s93, s3, 0
	v_cmp_lt_u32_e64 s[6:7], v47, v64
	v_cmp_lt_u32_e64 s[62:63], v2, v64
	s_lshl_b32 s3, s1, 15
	s_lshl_b32 s1, s1, 2
	v_mov_b32_e32 v2, v5
	v_mov_b32_e32 v3, v5
	v_mov_b32_e32 v6, v5
	v_mov_b32_e32 v7, v5
	v_mov_b32_e32 v8, v5
	v_mov_b32_e32 v9, v5
	v_mov_b32_e32 v10, v5
	v_mov_b32_e32 v11, v5
	v_mov_b32_e32 v12, v5
	v_mov_b32_e32 v13, v5
	v_mov_b32_e32 v14, v5
	v_mov_b32_e32 v15, v5
	v_lshlrev_b32_e32 v173, 2, v20
	v_mov_b64_e32 v[34:35], v[16:17]
	v_mov_b64_e32 v[50:51], v[16:17]
	s_add_i32 s93, s93, 0x20c00
	v_cmp_lt_u32_e64 s[56:57], v56, v64
	v_cmp_lt_u32_e64 s[60:61], v61, v64
	v_cmp_lt_u32_e64 s[64:65], v60, v64
	s_lshl_b32 s95, s2, 13
	s_sub_i32 s96, 0x30000, s3
	s_sub_i32 s97, s2, s1
	s_sub_i32 s1, 0, s1
	v_mov_b32_e32 v52, 0
	s_mov_b32 s33, 28
	v_mov_b64_e32 v[32:33], v[14:15]
	v_mov_b64_e32 v[30:31], v[12:13]
	v_mov_b64_e32 v[28:29], v[10:11]
	v_mov_b64_e32 v[26:27], v[8:9]
	v_mov_b64_e32 v[24:25], v[6:7]
	v_mov_b64_e32 v[22:23], v[4:5]
	v_mov_b64_e32 v[20:21], v[2:3]
	v_mov_b64_e32 v[48:49], v[14:15]
	v_mov_b64_e32 v[46:47], v[12:13]
	v_mov_b64_e32 v[44:45], v[10:11]
	v_mov_b64_e32 v[42:43], v[8:9]
	v_mov_b64_e32 v[40:41], v[6:7]
	v_mov_b64_e32 v[38:39], v[4:5]
	v_mov_b64_e32 v[36:37], v[2:3]
	v_cmp_lt_u32_e64 s[66:67], v54, v64
	v_cmp_lt_u32_e64 s[68:69], v63, v64
	v_cmp_lt_u32_e64 s[70:71], v55, v64
	v_cmp_eq_u32_e64 s[72:73], 0, v53
	s_mov_b64 s[74:75], 0
	s_add_i32 s89, s1, s33
	s_waitcnt lgkmcnt(0)
	s_barrier
	s_branch .LBB0_942

; #define LAS __attribute__((address_space(3)))
; __device__ __forceinline__ void conv_load(ConvRegs& c, const Args& a, size_t rowq, int col, int lane) {
; #pragma unroll
;     for (int i = 0; i < 4; ++i) { const size_t grow = rowq + i * 8 + (lane >> 3);
;         c.k[i] = *(const u32x4*)((const bf16*)(a.ws + WS_K) + grow * D + col + (lane & 7) * 8); c.v[i] = *(const u32x4*)((const bf16*)(a.ws + WS_V) + grow * D + col + (lane & 7) * 8); }
; }
; template <int TYPE>
; __device__ __forceinline__ void conv_store(const ConvRegs& c, const Args& a, int l, int h, size_t rowq, int lane) {
; #pragma unroll
;     for (int i = 0; i < 4; ++i) { const size_t grow = rowq + i * 8 + (lane >> 3);
;         float* ko = a.out + (TYPE == 0 ? O_FKP : O_SKP) + ((size_t)l * MP + grow) * W + h * HD + (lane & 7) * 8;
;         float* vo = a.out + (TYPE == 0 ? O_FVP : O_SVP) + ((size_t)l * MP + grow) * W + h * HD + (lane & 7) * 8;
;         const u32x4 kw = c.k[i], vw = c.v[i];
;         __builtin_nontemporal_store((f32x4){bflo(kw.x), bfhi(kw.x), bflo(kw.y), bfhi(kw.y)}, (f32x4*)ko); __builtin_nontemporal_store((f32x4){bflo(kw.z), bfhi(kw.z), bflo(kw.w), bfhi(kw.w)}, (f32x4*)(ko + 4));
;         __builtin_nontemporal_store((f32x4){bflo(vw.x), bfhi(vw.x), bflo(vw.y), bfhi(vw.y)}, (f32x4*)vo); __builtin_nontemporal_store((f32x4){bflo(vw.z), bfhi(vw.z), bflo(vw.w), bfhi(vw.w)}, (f32x4*)(vo + 4)); }
; }
; __device__ __forceinline__ void prompt_unit_fox(const Args& a, int l, int b, int h, int qb, LAS unsigned char* lds) {
;     ...
;     bf16x8 qr[4];
;     { const bf16* Qw = (const bf16*)(a.ws + WS_Q) + (rowb + q0 + wid * 32 + r32) * D + col;
; #pragma unroll
;       for (int d0 = 0; d0 < 4; ++d0) qr[d0] = *(const bf16x8*)(Qw + d0 * 16 + hi * 8); }
;     const lds_cptr vp0 = (lds_cptr)lds + F_V + ((lane >> 4) & 1) * 32 + (lane & 3) * 8 + (4 * hi + ((lane & 15) >> 2)) * 64;
;     const int ql = 32 * (wid & 1) + r32, qlim = ql + 1;
;     LAS float* wsf = (LAS float*)(lds + F_WSF) + wid * 64;
;     FoxState st; st.m = 0.f; st.l = 0.f; st.mq = (bf16x8){}; st.o[0] = (f32x16){}; st.o[1] = (f32x16){};
;     PairP pp; bool pending = false;
; #pragma unroll
;     for (int i = 0; i < 8; ++i) pp.w[i] = (u32x4){0u, 0u, 0u, 0u};
;     { ConvRegs cv; conv_load(cv, a, rowb + q0 + wid * 32, col, lane); conv_store<0>(cv, a, l, h, rowb + q0 + wid * 32, lane); }
.LBB0_963:
	v_writelane_b32 v242, s16, 32
	s_or_b64 exec, exec, s[2:3]
	s_lshl_b32 s0, s0, 2
	s_ashr_i32 s2, s6, 7
	s_add_i32 s2, s2, s0
	s_ashr_i32 s0, s2, 1
	s_cmp_lt_i32 s1, 4
	s_cselect_b64 s[90:91], -1, 0
	s_lshl_b32 s2, s8, 11
	s_lshl_b32 s3, s1, 5
	s_or_b32 s2, s9, s2
	s_ashr_i32 s8, s3, 31
	s_add_u32 s79, s3, s2
	v_and_b32_e32 v180, 31, v19
	s_addc_u32 s10, s8, 0
	v_or_b32_e32 v168, s79, v180
	v_mov_b32_e32 v169, s10
	v_readlane_b32 s8, v242, 28
	v_lshlrev_b64 v[2:3], 11, v[168:169]
	v_readlane_b32 s9, v242, 29
	v_lshrrev_b32_e32 v21, 5, v20
	s_lshl_b32 s74, s7, 1
	v_lshl_add_u64 v[2:3], s[8:9], 0, v[2:3]
	s_mov_b32 s75, s87
	v_lshl_add_u64 v[2:3], v[2:3], 0, s[74:75]
	v_lshlrev_b32_e32 v174, 4, v21
	v_mov_b32_e32 v175, v5
	v_lshl_add_u64 v[2:3], v[2:3], 0, v[174:175]
	global_load_dwordx4 v[6:9], v[2:3], off
	global_load_dwordx4 v[10:13], v[2:3], off offset:32
	global_load_dwordx4 v[14:17], v[2:3], off offset:64
	global_load_dwordx4 v[116:119], v[2:3], off offset:96
	v_lshlrev_b32_e32 v2, 1, v19
	v_and_b32_e32 v2, 32, v2
	v_add_u32_e32 v3, 0, v2
	v_lshlrev_b32_e32 v2, 2, v21
	v_lshrrev_b32_e32 v4, 2, v19
	v_and_or_b32 v4, v4, 3, v2
	v_lshlrev_b32_e32 v4, 6, v4
	s_and_b32 s2, s6, 0x3fffffc0
	v_add3_u32 v175, v3, v1, v4
	s_lshl_b32 s2, s2, 2
	v_lshrrev_b32_e32 v1, 3, v20
	v_and_or_b32 v3, s3, 32, v180
	s_add_i32 s89, s2, 0
	v_or_b32_e32 v168, s79, v1
	v_readlane_b32 s2, v242, 20
	v_lshlrev_b32_e32 v4, 3, v20
	v_lshlrev_b64 v[176:177], 11, v[168:169]
	v_readlane_b32 s3, v242, 21
	v_readlane_b32 s8, v242, 22
	v_and_b32_e32 v178, 56, v4
	v_lshl_add_u64 v[22:23], s[2:3], 0, v[176:177]
	v_readlane_b32 s9, v242, 23
	v_lshl_add_u64 v[22:23], v[22:23], 0, s[74:75]
	v_mov_b32_e32 v4, v178
	v_lshl_add_u64 v[26:27], s[8:9], 0, v[176:177]
	v_lshl_add_u64 v[22:23], v[22:23], 0, v[4:5]
	v_lshl_add_u64 v[26:27], v[26:27], 0, s[74:75]
	v_or_b32_e32 v34, 0x4000, v176
	v_mov_b32_e32 v35, v177
	global_load_dwordx2 v[24:25], v[22:23], off offset:64
	global_load_dwordx2 v[22:23], v[22:23], off
	v_lshl_add_u64 v[26:27], v[26:27], 0, v[4:5]
	v_lshl_add_u64 v[30:31], s[2:3], 0, v[34:35]
	global_load_dwordx2 v[28:29], v[26:27], off offset:64
	global_load_dwordx2 v[26:27], v[26:27], off
	v_lshl_add_u64 v[30:31], v[30:31], 0, s[74:75]
	v_lshl_add_u64 v[30:31], v[30:31], 0, v[4:5]
	global_load_dwordx2 v[32:33], v[30:31], off offset:64
	global_load_dwordx2 v[30:31], v[30:31], off
	v_lshl_add_u64 v[34:35], s[8:9], 0, v[34:35]
	v_lshl_add_u64 v[34:35], v[34:35], 0, s[74:75]
	v_lshl_add_u64 v[34:35], v[34:35], 0, v[4:5]
	global_load_dwordx2 v[36:37], v[34:35], off offset:64
	global_load_dwordx2 v[34:35], v[34:35], off
	v_or_b32_e32 v42, 0x8000, v176
	v_mov_b32_e32 v43, v177
	v_lshl_add_u64 v[38:39], s[2:3], 0, v[42:43]
	v_lshl_add_u64 v[38:39], v[38:39], 0, s[74:75]
	v_lshl_add_u64 v[38:39], v[38:39], 0, v[4:5]
	global_load_dwordx2 v[40:41], v[38:39], off offset:64
	global_load_dwordx2 v[38:39], v[38:39], off
	v_lshl_add_u64 v[42:43], s[8:9], 0, v[42:43]
	v_lshl_add_u64 v[42:43], v[42:43], 0, s[74:75]
	v_lshl_add_u64 v[42:43], v[42:43], 0, v[4:5]
	global_load_dwordx2 v[44:45], v[42:43], off offset:64
	global_load_dwordx2 v[42:43], v[42:43], off
	v_or_b32_e32 v50, 0xc000, v176
	v_mov_b32_e32 v51, v177
	v_lshl_add_u64 v[46:47], s[2:3], 0, v[50:51]
	v_lshl_add_u64 v[46:47], v[46:47], 0, s[74:75]
	v_lshl_add_u64 v[46:47], v[46:47], 0, v[4:5]
	global_load_dwordx2 v[48:49], v[46:47], off offset:64
	global_load_dwordx2 v[46:47], v[46:47], off
	v_lshl_add_u64 v[50:51], s[8:9], 0, v[50:51]
	v_lshl_add_u64 v[50:51], v[50:51], 0, s[74:75]
	v_lshl_add_u64 v[50:51], v[50:51], 0, v[4:5]
	global_load_dwordx2 v[52:53], v[50:51], off offset:64
	global_load_dwordx2 v[50:51], v[50:51], off
	s_add_i32 s89, s89, 0x1a000
	s_add_u32 s2, s79, 0x10000
	v_writelane_b32 v242, s10, 34
	s_addc_u32 s3, s10, 0
	v_or_b32_e32 v54, s2, v1
	v_mov_b32_e32 v55, s3
	v_readlane_b32 s2, v242, 26
	v_lshlrev_b64 v[54:55], 11, v[54:55]
	v_readlane_b32 s3, v242, 27
	s_lshl_b32 s92, s7, 2
	s_mov_b32 s93, s87
	v_lshl_add_u64 v[56:57], s[2:3], 0, v[54:55]
	v_readlane_b32 s2, v242, 43
	v_readlane_b32 s3, v242, 44
	v_lshl_add_u64 v[56:57], v[56:57], 0, s[92:93]
	v_lshlrev_b32_e32 v4, 1, v178
	v_lshl_add_u64 v[54:55], s[2:3], 0, v[54:55]
	v_lshl_add_u64 v[54:55], v[54:55], 0, s[92:93]
	v_lshl_add_u64 v[58:59], v[56:57], 0, v[4:5]
	v_lshl_add_u64 v[60:61], v[54:55], 0, v[4:5]
	v_or_b32_e32 v4, 32, v2
	v_cmp_gt_u32_e64 s[10:11], v4, v3
	v_or_b32_e32 v4, 33, v2
	v_cmp_gt_u32_e64 s[14:15], v4, v3
	v_or_b32_e32 v4, 2, v2
	v_cmp_gt_u32_e64 s[16:17], v4, v3
	v_or_b32_e32 v4, 34, v2
	v_cmp_gt_u32_e64 s[18:19], v4, v3
	v_or_b32_e32 v4, 3, v2
	v_cmp_gt_u32_e64 s[20:21], v4, v3
	v_or_b32_e32 v4, 35, v2
	v_cmp_gt_u32_e64 s[22:23], v4, v3
	v_or_b32_e32 v4, 8, v2
	s_mov_b64 s[2:3], 0x4000
	v_cmp_gt_u32_e64 s[24:25], v4, v3
	v_or_b32_e32 v4, 40, v2
	v_cmp_gt_u32_e64 s[26:27], v4, v3
	v_or_b32_e32 v4, 9, v2
	v_cmp_gt_u32_e64 s[28:29], v4, v3
	v_or_b32_e32 v4, 41, v2
	v_cmp_gt_u32_e64 s[30:31], v4, v3
	v_or_b32_e32 v4, 10, v2
	v_cmp_gt_u32_e64 s[34:35], v4, v3
	v_or_b32_e32 v4, 42, v2
	v_cmp_gt_u32_e64 s[36:37], v4, v3
	v_or_b32_e32 v4, 11, v2
	v_cmp_gt_u32_e64 s[38:39], v4, v3
	v_or_b32_e32 v4, 43, v2
	v_cmp_gt_u32_e64 s[40:41], v4, v3
	s_waitcnt vmcnt(0)
; #define LAS __attribute__((address_space(3)))
; __device__ __forceinline__ float bflo(unsigned w) { return __uint_as_float(w << 16); }
; __device__ __forceinline__ float bfhi(unsigned w) { return __uint_as_float(w & 0xffff0000u); }
; #define ATT_WAIT_BAR() asm volatile("s_waitcnt vmcnt(0) lgkmcnt(0)\n\ts_barrier" ::: "memory")
; template <int TYPE>
; __device__ __forceinline__ void conv_store(const ConvRegs& c, const Args& a, int l, int h, size_t rowq, int lane) {
; #pragma unroll
;     for (int i = 0; i < 4; ++i) { const size_t grow = rowq + i * 8 + (lane >> 3);
;         float* ko = a.out + (TYPE == 0 ? O_FKP : O_SKP) + ((size_t)l * MP + grow) * W + h * HD + (lane & 7) * 8;
;         float* vo = a.out + (TYPE == 0 ? O_FVP : O_SVP) + ((size_t)l * MP + grow) * W + h * HD + (lane & 7) * 8;
;         const u32x4 kw = c.k[i], vw = c.v[i];
;         __builtin_nontemporal_store((f32x4){bflo(kw.x), bfhi(kw.x), bflo(kw.y), bfhi(kw.y)}, (f32x4*)ko); __builtin_nontemporal_store((f32x4){bflo(kw.z), bfhi(kw.z), bflo(kw.w), bfhi(kw.w)}, (f32x4*)(ko + 4));
;         __builtin_nontemporal_store((f32x4){bflo(vw.x), bfhi(vw.x), bflo(vw.y), bfhi(vw.y)}, (f32x4*)vo); __builtin_nontemporal_store((f32x4){bflo(vw.z), bfhi(vw.z), bflo(vw.w), bfhi(vw.w)}, (f32x4*)(vo + 4)); }
; }
; __device__ __forceinline__ void prompt_unit_fox(const Args& a, int l, int b, int h, int qb, LAS unsigned char* lds) {
;     ...
;     const lds_cptr vp0 = (lds_cptr)lds + F_V + ((lane >> 4) & 1) * 32 + (lane & 3) * 8 + (4 * hi + ((lane & 15) >> 2)) * 64;
;     const int ql = 32 * (wid & 1) + r32, qlim = ql + 1;
;     LAS float* wsf = (LAS float*)(lds + F_WSF) + wid * 64;
;     FoxState st; st.m = 0.f; st.l = 0.f; st.mq = (bf16x8){}; st.o[0] = (f32x16){}; st.o[1] = (f32x16){};
;     PairP pp; bool pending = false;
; #pragma unroll
;     for (int i = 0; i < 8; ++i) pp.w[i] = (u32x4){0u, 0u, 0u, 0u};
;     { ConvRegs cv; conv_load(cv, a, rowb + q0 + wid * 32, col, lane); conv_store<0>(cv, a, l, h, rowb + q0 + wid * 32, lane); }
;     int slot = 0, pslot = 0;
;     ...
;         ATT_WAIT_BAR();
	v_lshlrev_b32_e32 v54, 16, v22
	v_and_b32_e32 v55, 0xffff0000, v22
	v_lshlrev_b32_e32 v56, 16, v23
	v_and_b32_e32 v57, 0xffff0000, v23
	v_lshlrev_b32_e32 v22, 16, v24
	v_and_b32_e32 v23, 0xffff0000, v24
	v_lshlrev_b32_e32 v24, 16, v25
	v_and_b32_e32 v25, 0xffff0000, v25
	global_store_dwordx4 v[58:59], v[22:25], off offset:128
	v_or_b32_e32 v4, 16, v2
	v_cmp_gt_u32_e64 s[42:43], v4, v3
	v_lshlrev_b32_e32 v22, 16, v26
	v_and_b32_e32 v23, 0xffff0000, v26
	v_lshlrev_b32_e32 v24, 16, v27
	v_and_b32_e32 v25, 0xffff0000, v27
	global_store_dwordx4 v[60:61], v[22:25], off
	v_lshl_add_u64 v[26:27], v[58:59], 0, s[2:3]
	v_or_b32_e32 v4, 48, v2
	v_lshlrev_b32_e32 v22, 16, v28
	v_and_b32_e32 v23, 0xffff0000, v28
	v_lshlrev_b32_e32 v24, 16, v29
	v_and_b32_e32 v25, 0xffff0000, v29
	v_lshl_add_u64 v[28:29], v[60:61], 0, s[2:3]
	s_movk_i32 s2, 0x4000
	global_store_dwordx4 v[60:61], v[22:25], off offset:128
	v_cmp_gt_u32_e64 s[44:45], v4, v3
	v_or_b32_e32 v4, 17, v2
	v_lshlrev_b32_e32 v22, 16, v30
	v_and_b32_e32 v23, 0xffff0000, v30
	v_add_co_u32_e32 v30, vcc, s2, v58
	v_lshlrev_b32_e32 v24, 16, v31
	v_and_b32_e32 v25, 0xffff0000, v31
	v_addc_co_u32_e32 v31, vcc, 0, v59, vcc
	global_store_dwordx4 v[30:31], v[22:25], off
	v_cmp_gt_u32_e64 s[46:47], v4, v3
	v_or_b32_e32 v4, 49, v2
	v_lshlrev_b32_e32 v22, 16, v32
	v_and_b32_e32 v23, 0xffff0000, v32
	v_lshlrev_b32_e32 v24, 16, v33
	v_and_b32_e32 v25, 0xffff0000, v33
	global_store_dwordx4 v[26:27], v[22:25], off offset:128
	v_add_co_u32_e32 v26, vcc, s2, v60
	s_nop 0
	v_lshlrev_b32_e32 v22, 16, v34
	v_and_b32_e32 v23, 0xffff0000, v34
	v_lshlrev_b32_e32 v24, 16, v35
	v_and_b32_e32 v25, 0xffff0000, v35
	v_addc_co_u32_e32 v27, vcc, 0, v61, vcc
	global_store_dwordx4 v[26:27], v[22:25], off
	s_mov_b64 s[2:3], 0x8000
	v_lshl_add_u64 v[26:27], v[58:59], 0, s[2:3]
	v_lshlrev_b32_e32 v22, 16, v36
	v_and_b32_e32 v23, 0xffff0000, v36
	v_lshlrev_b32_e32 v24, 16, v37
	v_and_b32_e32 v25, 0xffff0000, v37
	global_store_dwordx4 v[28:29], v[22:25], off offset:128
	v_lshl_add_u64 v[28:29], v[60:61], 0, s[2:3]
	s_mov_b32 s2, 0x8000
	v_add_co_u32_e32 v30, vcc, s2, v58
	v_lshlrev_b32_e32 v22, 16, v38
	v_and_b32_e32 v23, 0xffff0000, v38
	v_lshlrev_b32_e32 v24, 16, v39
	v_and_b32_e32 v25, 0xffff0000, v39
	v_addc_co_u32_e32 v31, vcc, 0, v59, vcc
	global_store_dwordx4 v[30:31], v[22:25], off
	v_cmp_gt_u32_e64 s[48:49], v4, v3
	v_or_b32_e32 v4, 18, v2
	v_lshlrev_b32_e32 v22, 16, v40
	v_and_b32_e32 v23, 0xffff0000, v40
	v_lshlrev_b32_e32 v24, 16, v41
	v_and_b32_e32 v25, 0xffff0000, v41
	global_store_dwordx4 v[26:27], v[22:25], off offset:128
	v_add_co_u32_e32 v26, vcc, s2, v60
	v_cmp_gt_u32_e64 s[50:51], v4, v3
	v_or_b32_e32 v4, 50, v2
	v_lshlrev_b32_e32 v22, 16, v42
	v_and_b32_e32 v23, 0xffff0000, v42
	v_lshlrev_b32_e32 v24, 16, v43
	v_and_b32_e32 v25, 0xffff0000, v43
	v_addc_co_u32_e32 v27, vcc, 0, v61, vcc
	v_cmp_gt_u32_e64 s[52:53], v4, v3
	v_or_b32_e32 v4, 19, v2
	global_store_dwordx4 v[26:27], v[22:25], off
	s_mov_b64 s[2:3], 0xc000
	v_cmp_gt_u32_e64 s[54:55], v4, v3
	v_lshlrev_b32_e32 v22, 16, v44
	v_and_b32_e32 v23, 0xffff0000, v44
	v_lshlrev_b32_e32 v24, 16, v45
	v_and_b32_e32 v25, 0xffff0000, v45
	v_or_b32_e32 v4, 51, v2
	global_store_dwordx4 v[28:29], v[22:25], off offset:128
	v_lshl_add_u64 v[26:27], v[58:59], 0, s[2:3]
	v_lshl_add_u64 v[28:29], v[60:61], 0, s[2:3]
	s_mov_b32 s2, 0xc000
	v_cmp_gt_u32_e64 s[56:57], v4, v3
	v_or_b32_e32 v4, 24, v2
	v_add_co_u32_e32 v30, vcc, s2, v58
	v_cmp_gt_u32_e64 s[58:59], v4, v3
	v_or_b32_e32 v4, 56, v2
	v_lshlrev_b32_e32 v22, 16, v46
	v_and_b32_e32 v23, 0xffff0000, v46
	v_lshlrev_b32_e32 v24, 16, v47
	v_and_b32_e32 v25, 0xffff0000, v47
	v_addc_co_u32_e32 v31, vcc, 0, v59, vcc
	v_cmp_gt_u32_e64 s[60:61], v4, v3
	v_or_b32_e32 v4, 25, v2
	global_store_dwordx4 v[30:31], v[22:25], off
	v_cmp_gt_u32_e64 s[62:63], v4, v3
	v_or_b32_e32 v4, 57, v2
	v_lshlrev_b32_e32 v22, 16, v48
	v_and_b32_e32 v23, 0xffff0000, v48
	v_lshlrev_b32_e32 v24, 16, v49
	v_and_b32_e32 v25, 0xffff0000, v49
	global_store_dwordx4 v[26:27], v[22:25], off offset:128
	v_add_co_u32_e32 v26, vcc, s2, v60
	s_add_i32 s2, 0, 0x18000
	v_cmp_gt_u32_e64 s[64:65], v4, v3
	v_or_b32_e32 v4, 26, v2
	v_lshlrev_b32_e32 v22, 16, v50
	v_and_b32_e32 v23, 0xffff0000, v50
	v_lshlrev_b32_e32 v24, 16, v51
	v_and_b32_e32 v25, 0xffff0000, v51
	v_addc_co_u32_e32 v27, vcc, 0, v61, vcc
	v_add_u32_e32 v186, s2, v174
	s_add_i32 s2, 0, 0x1a800
	v_cmp_gt_u32_e64 s[66:67], v4, v3
	v_or_b32_e32 v4, 58, v2
	v_mov_b32_e32 v66, v5
	v_mov_b32_e32 v67, v5
	global_store_dwordx4 v[58:59], v[54:57], off
	global_store_dwordx4 v[26:27], v[22:25], off
	s_bitcmp1_b32 s6, 7
	v_cmp_gt_u32_e64 s[6:7], 32, v20
	v_lshlrev_b32_e32 v22, 16, v52
	v_and_b32_e32 v23, 0xffff0000, v52
	v_lshlrev_b32_e32 v24, 16, v53
	v_and_b32_e32 v25, 0xffff0000, v53
	v_cmp_gt_u32_e64 s[8:9], v2, v3
	v_cmp_lt_u32_e64 s[12:13], v2, v3
	v_cmp_gt_u32_e64 s[68:69], v4, v3
	v_or_b32_e32 v4, 27, v2
	v_or_b32_e32 v2, 59, v2
	v_mov_b32_e32 v52, v5
	v_mov_b32_e32 v53, v5
	v_mov_b32_e32 v54, v5
	v_mov_b32_e32 v55, v5
	v_mov_b32_e32 v56, v5
	v_mov_b32_e32 v57, v5
	v_mov_b32_e32 v58, v5
	v_mov_b32_e32 v59, v5
	v_mov_b32_e32 v60, v5
	v_mov_b32_e32 v61, v5
	v_mov_b32_e32 v62, v5
	v_mov_b32_e32 v63, v5
	v_mov_b32_e32 v64, v5
	v_mov_b32_e32 v65, v5
	v_mov_b64_e32 v[82:83], v[66:67]
	s_mov_b32 s75, 0
	v_lshl_add_u32 v188, v180, 3, s2
	s_cselect_b64 s[94:95], -1, 0
	v_lshlrev_b32_e32 v182, 10, v21
	v_lshlrev_b32_e32 v189, 4, v180
	v_cndmask_b32_e64 v122, 0, v183, s[6:7]
	v_cndmask_b32_e64 v121, 0, -1.0, s[6:7]
	v_mov_b32_e32 v120, v5
	v_mov_b32_e32 v123, v5
	v_cmp_gt_u32_e64 s[70:71], v4, v3
	v_cmp_gt_u32_e64 s[72:73], v2, v3
	v_lshl_add_u32 v184, v180, 2, s89
	v_mov_b32_e32 v156, v5
	v_mov_b32_e32 v157, v5
	v_mov_b32_e32 v158, v5
	v_mov_b32_e32 v159, v5
	v_mov_b32_e32 v192, 0
	s_mov_b64 s[2:3], 0
	v_mov_b32_e32 v124, 0
	v_mov_b32_e32 v125, 0
	v_mov_b32_e32 v126, 0
	v_mov_b32_e32 v127, 0
	v_mov_b32_e32 v128, 0
	v_mov_b32_e32 v129, 0
	v_mov_b32_e32 v130, 0
	v_mov_b32_e32 v131, 0
	v_mov_b32_e32 v132, 0
	v_mov_b32_e32 v133, 0
	v_mov_b32_e32 v134, 0
	v_mov_b32_e32 v135, 0
	v_mov_b32_e32 v136, 0
	v_mov_b32_e32 v137, 0
	v_mov_b32_e32 v138, 0
	v_mov_b32_e32 v139, 0
	v_mov_b32_e32 v140, 0
	v_mov_b32_e32 v141, 0
	v_mov_b32_e32 v142, 0
	v_mov_b32_e32 v143, 0
	v_mov_b32_e32 v144, 0
	v_mov_b32_e32 v145, 0
	v_mov_b32_e32 v146, 0
	v_mov_b32_e32 v147, 0
	v_mov_b32_e32 v148, 0
	v_mov_b32_e32 v149, 0
	v_mov_b32_e32 v150, 0
	v_mov_b32_e32 v151, 0
	v_mov_b32_e32 v152, 0
	v_mov_b32_e32 v153, 0
	v_mov_b32_e32 v154, 0
	v_mov_b32_e32 v155, 0
	v_cndmask_b32_e64 v2, 0, v185, s[6:7]
	s_mov_b32 s93, 0
	v_mov_b64_e32 v[80:81], v[64:65]
	v_mov_b64_e32 v[78:79], v[62:63]
	v_mov_b64_e32 v[76:77], v[60:61]
	v_mov_b64_e32 v[74:75], v[58:59]
	v_mov_b64_e32 v[72:73], v[56:57]
	v_mov_b64_e32 v[70:71], v[54:55]
	v_mov_b64_e32 v[68:69], v[52:53]
	v_mov_b32_e32 v193, 0
	global_store_dwordx4 v[28:29], v[22:25], off offset:128
	s_waitcnt vmcnt(16) lgkmcnt(0)
	s_barrier
	s_branch .Lfox_top_l1
